# write-through (sc0 sc1) on 16-byte stores of P0,P1,P2,P4 and attention O, ahead of the full grid barriers
# speedup vs baseline: 1.0029x; 1.0029x over previous
.LBB0_12:
	s_waitcnt vmcnt(0)
	v_mul_f32_e32 v6, v6, v10
	ds_write2_b32 v1, v2, v6 offset0:48 offset1:56
	v_mul_f32_e32 v2, v7, v10
	ds_write2_b32 v1, v3, v2 offset0:114 offset1:122
	v_mul_f32_e32 v2, v8, v10
	ds_write2_b32 v1, v4, v2 offset0:180 offset1:188
	v_mul_f32_e32 v2, v9, v10
	ds_write2_b32 v1, v5, v2 offset0:246 offset1:254
	s_waitcnt lgkmcnt(0)
	s_mulk_i32 s6, 0xea00
	s_add_i32 s0, s16, s6
	ds_read2_b64 v[2:5], v53 offset1:1
	ds_read2_b64 v[6:9], v53 offset0:2 offset1:3
	s_and_b32 s0, s0, 0xffffff00
	s_and_b32 s1, s12, 0x60
	s_or_b32 s0, s1, s0
	v_or_b32_e32 v10, s0, v34
	v_ashrrev_i32_e32 v11, 31, v10
	s_waitcnt lgkmcnt(1)
	v_cvt_pk_bf16_f32 v2, v2, v3
	v_cvt_pk_bf16_f32 v3, v4, v5
	s_waitcnt lgkmcnt(0)
	v_cvt_pk_bf16_f32 v4, v6, v7
	v_cvt_pk_bf16_f32 v5, v8, v9
	ds_read2_b64 v[6:9], v54 offset1:1
	v_lshlrev_b64 v[16:17], 11, v[10:11]
	ds_read2_b64 v[10:13], v55 offset1:1
	v_lshl_add_u64 v[14:15], s[4:5], 1, v[40:41]
	v_lshl_add_u64 v[16:17], v[14:15], 0, v[16:17]
	global_store_dwordx4 v[16:17], v[2:5], off sc0 sc1
	s_waitcnt lgkmcnt(0)
	s_nop 0
	v_cvt_pk_bf16_f32 v4, v10, v11
	v_or_b32_e32 v10, s0, v50
	v_cvt_pk_bf16_f32 v2, v6, v7
	v_cvt_pk_bf16_f32 v3, v8, v9
	v_ashrrev_i32_e32 v11, 31, v10
	ds_read2_b64 v[6:9], v56 offset1:1
	v_cvt_pk_bf16_f32 v5, v12, v13
	v_lshlrev_b64 v[16:17], 11, v[10:11]
	ds_read2_b64 v[10:13], v57 offset1:1
	v_lshl_add_u64 v[16:17], v[14:15], 0, v[16:17]
	global_store_dwordx4 v[16:17], v[2:5], off sc0 sc1
	s_waitcnt lgkmcnt(1)
	s_nop 0
	v_cvt_pk_bf16_f32 v2, v6, v7
	v_cvt_pk_bf16_f32 v3, v8, v9
	ds_read2_b64 v[6:9], v58 offset1:1
	s_waitcnt lgkmcnt(1)
	v_cvt_pk_bf16_f32 v4, v10, v11
	v_or_b32_e32 v10, s0, v51
	v_ashrrev_i32_e32 v11, 31, v10
	v_cvt_pk_bf16_f32 v5, v12, v13
	v_lshlrev_b64 v[16:17], 11, v[10:11]
	ds_read2_b64 v[10:13], v59 offset1:1
	v_lshl_add_u64 v[16:17], v[14:15], 0, v[16:17]
	global_store_dwordx4 v[16:17], v[2:5], off sc0 sc1
	s_waitcnt lgkmcnt(1)
	s_nop 0
	v_cvt_pk_bf16_f32 v2, v6, v7
	v_or_b32_e32 v6, s0, v52
	v_ashrrev_i32_e32 v7, 31, v6
	v_lshlrev_b64 v[6:7], 11, v[6:7]
	v_cvt_pk_bf16_f32 v3, v8, v9
	s_waitcnt lgkmcnt(0)
	v_cvt_pk_bf16_f32 v4, v10, v11
	v_cvt_pk_bf16_f32 v5, v12, v13
	v_lshl_add_u64 v[6:7], v[14:15], 0, v[6:7]
	global_store_dwordx4 v[6:7], v[2:5], off sc0 sc1
	s_waitcnt lgkmcnt(0)

.LBB0_14:
	s_cmpk_gt_i32 s38, 0x57f
	s_mov_b64 s[0:1], -1
	s_cbranch_scc0 .LBB0_28
	s_cmpk_gt_u32 s38, 0xaff
	s_cbranch_scc0 .LBB0_17
	s_add_i32 s1, s14, 0xfffea000
	s_and_b32 s0, s20, 0xfc0
	s_and_b32 s1, s1, 0x3e0
	v_or_b32_e32 v4, s0, v34
	s_lshl_b32 s6, s1, 2
	v_lshl_add_u64 v[2:3], v[42:43], 0, s[6:7]
	v_lshlrev_b32_e32 v36, 12, v4
	v_lshl_add_u64 v[26:27], v[2:3], 0, v[36:37]
	v_add_co_u32_e32 v6, vcc, s22, v26
	v_or_b32_e32 v36, s1, v34
	s_nop 0
	v_addc_co_u32_e32 v7, vcc, 0, v27, vcc
	v_add_co_u32_e32 v10, vcc, s23, v26
	global_load_dwordx4 v[2:5], v[26:27], off
	s_nop 0
	global_load_dwordx4 v[6:9], v[6:7], off
	v_addc_co_u32_e32 v11, vcc, 0, v27, vcc
	v_add_co_u32_e32 v14, vcc, s24, v26
	v_or_b32_e32 v48, s1, v50
	s_nop 0
	v_addc_co_u32_e32 v15, vcc, 0, v27, vcc
	v_add_co_u32_e32 v18, vcc, s25, v26
	global_load_dwordx4 v[10:13], v[10:11], off
	s_nop 0
	global_load_dwordx4 v[14:17], v[14:15], off
	v_addc_co_u32_e32 v19, vcc, 0, v27, vcc
	v_add_co_u32_e32 v22, vcc, s26, v26
	v_or_b32_e32 v49, s1, v51
	s_nop 0
	v_addc_co_u32_e32 v23, vcc, 0, v27, vcc
	v_add_co_u32_e32 v28, vcc, s27, v26
	global_load_dwordx4 v[18:21], v[18:19], off
	s_nop 0
	global_load_dwordx4 v[22:25], v[22:23], off
	v_addc_co_u32_e32 v29, vcc, 0, v27, vcc
	v_add_co_u32_e32 v30, vcc, s28, v26
	s_lshl_b32 s6, s0, 1
	s_nop 0
	v_addc_co_u32_e32 v31, vcc, 0, v27, vcc
	global_load_dwordx4 v[26:29], v[28:29], off
	s_nop 0
	global_load_dwordx4 v[30:33], v[30:31], off
	v_mul_u32_u24_e32 v36, 0xb00, v36
	v_mul_u32_u24_e32 v62, 0xb00, v48
	v_mul_u32_u24_e32 v64, 0xb00, v49
	v_lshl_add_u64 v[48:49], v[38:39], 0, s[6:7]
	v_lshlrev_b32_e32 v36, 1, v36
	v_lshl_add_u64 v[60:61], v[48:49], 0, v[36:37]
	v_lshlrev_b32_e32 v36, 1, v62
	v_lshl_add_u64 v[62:63], v[48:49], 0, v[36:37]
	v_lshlrev_b32_e32 v36, 1, v64
	s_waitcnt vmcnt(6)
	ds_write2_b32 v1, v2, v6 offset1:8
	ds_write2_b32 v1, v3, v7 offset0:66 offset1:74
	ds_write2_b32 v1, v4, v8 offset0:132 offset1:140
	ds_write2_b32 v1, v5, v9 offset0:198 offset1:206
	s_waitcnt vmcnt(4)
	ds_write2_b32 v1, v10, v14 offset0:16 offset1:24
	ds_write2_b32 v1, v11, v15 offset0:82 offset1:90
	ds_write2_b32 v1, v12, v16 offset0:148 offset1:156
	ds_write2_b32 v1, v13, v17 offset0:214 offset1:222
	s_waitcnt vmcnt(2)
	ds_write2_b32 v1, v18, v22 offset0:32 offset1:40
	ds_write2_b32 v1, v19, v23 offset0:98 offset1:106
	ds_write2_b32 v1, v20, v24 offset0:164 offset1:172
	ds_write2_b32 v1, v21, v25 offset0:230 offset1:238
	s_waitcnt vmcnt(0)
	ds_write2_b32 v1, v26, v30 offset0:48 offset1:56
	ds_write2_b32 v1, v27, v31 offset0:114 offset1:122
	ds_write2_b32 v1, v28, v32 offset0:180 offset1:188
	ds_write2_b32 v1, v29, v33 offset0:246 offset1:254
	s_waitcnt lgkmcnt(0)
	ds_read2_b64 v[2:5], v53 offset1:1
	ds_read2_b64 v[6:9], v53 offset0:2 offset1:3
	ds_read2_b64 v[10:13], v54 offset1:1
	ds_read2_b64 v[14:17], v55 offset1:1
	ds_read2_b64 v[18:21], v56 offset1:1
	ds_read2_b64 v[22:25], v57 offset1:1
	ds_read2_b64 v[26:29], v58 offset1:1
	s_waitcnt lgkmcnt(6)
	v_cvt_pk_bf16_f32 v2, v2, v3
	v_cvt_pk_bf16_f32 v3, v4, v5
	s_waitcnt lgkmcnt(5)
	v_cvt_pk_bf16_f32 v4, v6, v7
	v_cvt_pk_bf16_f32 v5, v8, v9
	s_waitcnt lgkmcnt(4)
	v_cvt_pk_bf16_f32 v6, v10, v11
	v_cvt_pk_bf16_f32 v7, v12, v13
	s_waitcnt lgkmcnt(3)
	v_cvt_pk_bf16_f32 v8, v14, v15
	v_cvt_pk_bf16_f32 v9, v16, v17
	global_store_dwordx4 v[60:61], v[2:5], off sc0 sc1
	global_store_dwordx4 v[62:63], v[6:9], off sc0 sc1
	ds_read2_b64 v[2:5], v59 offset1:1
	s_waitcnt lgkmcnt(3)
	v_cvt_pk_bf16_f32 v10, v18, v19
	v_cvt_pk_bf16_f32 v11, v20, v21
	s_waitcnt lgkmcnt(2)
	v_cvt_pk_bf16_f32 v12, v22, v23
	v_cvt_pk_bf16_f32 v13, v24, v25
	s_waitcnt lgkmcnt(0)
	v_cvt_pk_bf16_f32 v8, v2, v3
	v_or_b32_e32 v2, s1, v52
	v_mul_u32_u24_e32 v2, 0xb00, v2
	v_lshl_add_u64 v[6:7], v[48:49], 0, v[36:37]
	v_lshlrev_b32_e32 v36, 1, v2
	global_store_dwordx4 v[6:7], v[10:13], off sc0 sc1
	v_cvt_pk_bf16_f32 v6, v26, v27
	v_cvt_pk_bf16_f32 v7, v28, v29
	v_cvt_pk_bf16_f32 v9, v4, v5
	v_lshl_add_u64 v[2:3], v[48:49], 0, v[36:37]
	global_store_dwordx4 v[2:3], v[6:9], off sc0 sc1
	s_waitcnt lgkmcnt(0)
	s_mov_b64 s[0:1], 0

.LBB0_26:
	s_waitcnt vmcnt(0)
	v_mul_f32_e32 v6, v6, v18
	ds_write2_b32 v1, v2, v6 offset0:48 offset1:56
	v_mul_f32_e32 v2, v7, v18
	ds_write2_b32 v1, v3, v2 offset0:114 offset1:122
	v_mul_f32_e32 v2, v8, v18
	ds_write2_b32 v1, v4, v2 offset0:180 offset1:188
	v_mul_f32_e32 v2, v9, v18
	ds_write2_b32 v1, v5, v2 offset0:246 offset1:254
	s_waitcnt lgkmcnt(0)
	s_lshl_b32 s4, s1, 5
	s_lshl_b32 s1, s1, 6
	ds_read2_b64 v[2:5], v53 offset1:1
	ds_read2_b64 v[6:9], v53 offset0:2 offset1:3
	s_and_b32 s1, s1, 0x1f00
	s_and_b32 s4, s4, 0x60
	s_or_b32 s1, s1, s4
	s_bitset1_b32 s1, 7
	v_or_b32_e32 v10, s1, v34
	s_waitcnt lgkmcnt(1)
	v_cvt_pk_bf16_f32 v2, v2, v3
	v_cvt_pk_bf16_f32 v3, v4, v5
	s_waitcnt lgkmcnt(0)
	v_cvt_pk_bf16_f32 v4, v6, v7
	v_cvt_pk_bf16_f32 v5, v8, v9
	ds_read2_b64 v[6:9], v54 offset1:1
	v_lshlrev_b32_e32 v36, 11, v10
	ds_read2_b64 v[10:13], v55 offset1:1
	s_lshl_b32 s6, s0, 1
	v_lshl_add_u64 v[14:15], v[40:41], 0, s[6:7]
	v_lshl_add_u64 v[16:17], v[14:15], 0, v[36:37]
	global_store_dwordx4 v[16:17], v[2:5], off sc0 sc1
	s_waitcnt lgkmcnt(1)
	s_nop 0
	v_cvt_pk_bf16_f32 v2, v6, v7
	v_cvt_pk_bf16_f32 v3, v8, v9
	s_waitcnt lgkmcnt(0)
	v_cvt_pk_bf16_f32 v4, v10, v11
	v_or_b32_e32 v10, s1, v50
	ds_read2_b64 v[6:9], v56 offset1:1
	v_cvt_pk_bf16_f32 v5, v12, v13
	v_lshlrev_b32_e32 v36, 11, v10
	ds_read2_b64 v[10:13], v57 offset1:1
	v_lshl_add_u64 v[16:17], v[14:15], 0, v[36:37]
	global_store_dwordx4 v[16:17], v[2:5], off sc0 sc1
	s_waitcnt lgkmcnt(1)
	s_nop 0
	v_cvt_pk_bf16_f32 v2, v6, v7
	v_cvt_pk_bf16_f32 v3, v8, v9
	ds_read2_b64 v[6:9], v58 offset1:1
	s_waitcnt lgkmcnt(1)
	v_cvt_pk_bf16_f32 v4, v10, v11
	v_or_b32_e32 v10, s1, v51
	v_cvt_pk_bf16_f32 v5, v12, v13
	v_lshlrev_b32_e32 v36, 11, v10
	ds_read2_b64 v[10:13], v59 offset1:1
	v_lshl_add_u64 v[16:17], v[14:15], 0, v[36:37]
	global_store_dwordx4 v[16:17], v[2:5], off sc0 sc1
	s_waitcnt lgkmcnt(1)
	s_nop 0
	v_cvt_pk_bf16_f32 v2, v6, v7
	v_or_b32_e32 v6, s1, v52
	v_lshlrev_b32_e32 v36, 11, v6
	v_cvt_pk_bf16_f32 v3, v8, v9
	s_waitcnt lgkmcnt(0)
	v_cvt_pk_bf16_f32 v4, v10, v11
	v_cvt_pk_bf16_f32 v5, v12, v13
	v_lshl_add_u64 v[6:7], v[14:15], 0, v[36:37]
	global_store_dwordx4 v[6:7], v[2:5], off sc0 sc1
	s_waitcnt lgkmcnt(0)

.LBB0_44:
	s_ashr_i32 s13, s12, 31
	s_lshl_b64 s[0:1], s[12:13], 12
	v_lshl_add_u64 v[2:3], v[72:73], 0, s[0:1]
	global_load_dwordx4 v[22:25], v[2:3], off
	global_load_dwordx4 v[18:21], v[2:3], off offset:1024
	s_waitcnt lgkmcnt(2)
	global_load_dwordx4 v[14:17], v[2:3], off offset:2048
	s_waitcnt lgkmcnt(0)
	global_load_dwordx4 v[10:13], v[2:3], off offset:3072
	s_add_i32 s0, s12, s11
	s_cmpk_lt_i32 s0, 0x4000
	s_cselect_b64 s[30:31], -1, 0
	s_and_b64 s[14:15], s[30:31], exec
	s_cselect_b32 s14, s0, s12
	s_ashr_i32 s15, s14, 31
	s_lshl_b64 s[14:15], s[14:15], 12
	v_lshl_add_u64 v[2:3], v[72:73], 0, s[14:15]
	global_load_dwordx4 v[38:41], v[2:3], off
	global_load_dwordx4 v[42:45], v[2:3], off offset:1024
	global_load_dwordx4 v[34:37], v[2:3], off offset:2048
	global_load_dwordx4 v[62:65], v[2:3], off offset:3072
	s_add_i32 s16, s18, s12
	s_cmpk_lt_i32 s16, 0x4000
	s_cselect_b64 s[36:37], -1, 0
	s_and_b64 s[14:15], s[36:37], exec
	s_cselect_b32 s20, s16, s12
	s_ashr_i32 s21, s20, 31
	s_lshl_b64 s[20:21], s[20:21], 12
	v_lshl_add_u64 v[2:3], v[72:73], 0, s[20:21]
	global_load_dwordx4 v[58:61], v[2:3], off
	global_load_dwordx4 v[54:57], v[2:3], off offset:1024
	global_load_dwordx4 v[50:53], v[2:3], off offset:2048
	global_load_dwordx4 v[46:49], v[2:3], off offset:3072
	s_add_i32 s14, s19, s12
	s_cmpk_lt_i32 s14, 0x4000
	s_cselect_b64 s[28:29], -1, 0
	s_and_b64 s[20:21], s[28:29], exec
	s_cselect_b32 s20, s14, s12
	s_ashr_i32 s21, s20, 31
	s_lshl_b64 s[20:21], s[20:21], 12
	v_lshl_add_u64 v[2:3], v[72:73], 0, s[20:21]
	global_load_dwordx4 v[30:33], v[2:3], off
	global_load_dwordx4 v[26:29], v[2:3], off offset:1024
	global_load_dwordx4 v[6:9], v[2:3], off offset:2048
	s_nop 0
	global_load_dwordx4 v[2:5], v[2:3], off offset:3072
	v_mov_b32_e32 v67, 0
	v_mov_b32_e32 v82, 0
	v_mov_b32_e32 v83, 0
	s_lshl_b64 s[22:23], s[12:13], 11
	v_lshl_add_u64 v[80:81], v[68:69], 0, s[22:23]
	s_waitcnt vmcnt(15)
	v_mul_f32_e32 v84, v23, v23
	v_mul_f32_e32 v85, v25, v25
	s_waitcnt vmcnt(14)
	v_mul_f32_e32 v86, v19, v19
	v_mul_f32_e32 v87, v21, v21
	s_waitcnt vmcnt(13)
	v_mul_f32_e32 v88, v15, v15
	v_mul_f32_e32 v89, v17, v17
	v_fmac_f32_e32 v84, v22, v22
	v_fmac_f32_e32 v85, v24, v24
	v_fmac_f32_e32 v86, v18, v18
	v_fmac_f32_e32 v87, v20, v20
	v_cvt_pk_bf16_f32 v15, v14, v15
	v_cvt_pk_bf16_f32 v90, v16, v17
	s_waitcnt vmcnt(12)
	v_mul_f32_e32 v17, v11, v11
	v_mul_f32_e32 v91, v13, v13
	v_fmac_f32_e32 v88, v14, v14
	v_fmac_f32_e32 v89, v16, v16
	v_add_f32_e32 v14, v84, v85
	v_add_f32_e32 v16, v86, v87
	v_cvt_pk_bf16_f32 v19, v18, v19
	v_fmac_f32_e32 v17, v10, v10
	v_fmac_f32_e32 v91, v12, v12
	v_add_f32_e32 v18, v88, v89
	v_add_f32_e32 v14, v14, v16
	v_add_f32_e32 v17, v17, v91
	v_add_f32_e32 v14, v14, v18
	v_add_f32_e32 v14, v14, v17
	ds_bpermute_b32 v16, v74, v14
	v_cvt_pk_bf16_f32 v23, v22, v23
	v_cvt_pk_bf16_f32 v25, v24, v25
	v_cvt_pk_bf16_f32 v21, v20, v21
	v_cvt_pk_bf16_f32 v92, v10, v11
	v_cvt_pk_bf16_f32 v93, v12, v13
	v_cndmask_b32_e64 v11, v23, v19, s[6:7]
	v_cndmask_b32_e64 v13, v25, v21, s[6:7]
	v_cndmask_b32_e64 v10, v15, v92, s[6:7]
	v_mov_b32_dpp v67, v11 quad_perm:[1,0,3,2] row_mask:0xf bank_mask:0xf
	v_mov_b32_dpp v82, v13 quad_perm:[1,0,3,2] row_mask:0xf bank_mask:0xf
	v_mov_b32_dpp v83, v10 quad_perm:[1,0,3,2] row_mask:0xf bank_mask:0xf
	v_cndmask_b32_e64 v10, v67, v23, s[6:7]
	v_cndmask_b32_e64 v11, v82, v25, s[6:7]
	v_cndmask_b32_e64 v12, v19, v67, s[6:7]
	v_cndmask_b32_e64 v13, v21, v82, s[6:7]
	global_store_dwordx4 v[80:81], v[10:13], off sc0 sc1
	v_cndmask_b32_e64 v18, v83, v15, s[6:7]
	s_waitcnt vmcnt(11)
	v_mul_f32_e32 v15, v45, v45
	s_waitcnt lgkmcnt(0)
	v_add_f32_e32 v11, v14, v16
	ds_bpermute_b32 v12, v75, v11
	v_mul_f32_e32 v10, v39, v39
	v_mul_f32_e32 v13, v41, v41
	v_mul_f32_e32 v14, v43, v43
	s_waitcnt vmcnt(10)
	v_mul_f32_e32 v16, v35, v35
	s_waitcnt lgkmcnt(0)
	v_add_f32_e32 v11, v11, v12
	ds_bpermute_b32 v12, v76, v11
	v_mul_f32_e32 v17, v37, v37
	v_fmac_f32_e32 v10, v38, v38
	v_fmac_f32_e32 v13, v40, v40
	v_fmac_f32_e32 v14, v42, v42
	s_waitcnt lgkmcnt(0)
	v_add_f32_e32 v11, v11, v12
	ds_bpermute_b32 v12, v77, v11
	v_fmac_f32_e32 v15, v44, v44
	v_fmac_f32_e32 v16, v34, v34
	v_fmac_f32_e32 v17, v36, v36
	v_add_f32_e32 v10, v10, v13
	s_waitcnt lgkmcnt(0)
	v_add_f32_e32 v11, v11, v12
	ds_bpermute_b32 v12, v78, v11
	v_add_f32_e32 v13, v14, v15
	v_add_f32_e32 v14, v16, v17
	v_add_f32_e32 v10, v10, v13
	v_add_f32_e32 v10, v10, v14
	s_waitcnt lgkmcnt(0)
	v_add_f32_e32 v14, v11, v12
	s_waitcnt vmcnt(9)
	v_mul_f32_e32 v11, v63, v63
	v_mul_f32_e32 v12, v65, v65
	v_fmac_f32_e32 v11, v62, v62
	v_fmac_f32_e32 v12, v64, v64
	v_add_f32_e32 v11, v11, v12
	s_waitcnt vmcnt(8)
	v_mul_f32_e32 v12, v59, v59
	v_mul_f32_e32 v13, v61, v61
	v_fmac_f32_e32 v12, v58, v58
	v_fmac_f32_e32 v13, v60, v60
	v_add_f32_e32 v12, v12, v13
	s_waitcnt vmcnt(7)
	v_mul_f32_e32 v13, v55, v55
	v_mul_f32_e32 v16, v57, v57
	v_fmac_f32_e32 v13, v54, v54
	v_fmac_f32_e32 v16, v56, v56
	v_add_f32_e32 v13, v13, v16
	v_add_f32_e32 v12, v12, v13
	s_waitcnt vmcnt(6)
	v_mul_f32_e32 v13, v51, v51
	v_mul_f32_e32 v16, v53, v53
	v_fmac_f32_e32 v13, v50, v50
	v_fmac_f32_e32 v16, v52, v52
	v_add_f32_e32 v13, v13, v16
	v_add_f32_e32 v12, v12, v13
	s_waitcnt vmcnt(5)
	v_mul_f32_e32 v13, v47, v47
	v_mul_f32_e32 v16, v49, v49
	v_fmac_f32_e32 v13, v46, v46
	v_fmac_f32_e32 v16, v48, v48
	v_add_f32_e32 v13, v13, v16
	s_waitcnt vmcnt(4)
	v_mul_f32_e32 v16, v31, v31
	v_mul_f32_e32 v17, v33, v33
	v_fmac_f32_e32 v16, v30, v30
	v_fmac_f32_e32 v17, v32, v32
	v_add_f32_e32 v16, v16, v17
	s_waitcnt vmcnt(3)
	v_mul_f32_e32 v17, v27, v27
	v_mul_f32_e32 v22, v29, v29
	v_fmac_f32_e32 v17, v26, v26
	v_fmac_f32_e32 v22, v28, v28
	v_add_f32_e32 v17, v17, v22
	v_add_f32_e32 v16, v16, v17
	s_waitcnt vmcnt(2)
	v_mul_f32_e32 v17, v7, v7
	v_mul_f32_e32 v22, v9, v9
	v_fmac_f32_e32 v17, v6, v6
	v_fmac_f32_e32 v22, v8, v8
	v_add_f32_e32 v17, v17, v22
	v_add_f32_e32 v16, v16, v17
	s_waitcnt vmcnt(1)
	v_mul_f32_e32 v17, v3, v3
	v_mul_f32_e32 v22, v5, v5
	v_fmac_f32_e32 v17, v2, v2
	v_fmac_f32_e32 v22, v4, v4
	v_add_f32_e32 v17, v17, v22
	v_add_f32_e32 v10, v10, v11
	v_add_f32_e32 v12, v12, v13
	v_add_f32_e32 v16, v16, v17
	ds_bpermute_b32 v11, v74, v10
	ds_bpermute_b32 v13, v74, v12
	ds_bpermute_b32 v17, v74, v16
	ds_bpermute_b32 v15, v79, v14
	v_cndmask_b32_e64 v19, v90, v93, s[6:7]
	s_waitcnt lgkmcnt(3)
	v_add_f32_e32 v10, v10, v11
	s_waitcnt lgkmcnt(2)
	v_add_f32_e32 v12, v12, v13
	s_waitcnt lgkmcnt(1)
	v_add_f32_e32 v16, v16, v17
	ds_bpermute_b32 v11, v75, v10
	ds_bpermute_b32 v13, v75, v12
	ds_bpermute_b32 v17, v75, v16
	v_mov_b32_e32 v21, 0
	v_cndmask_b32_e64 v20, v92, v83, s[6:7]
	s_waitcnt lgkmcnt(2)
	v_add_f32_e32 v10, v10, v11
	s_waitcnt lgkmcnt(1)
	v_add_f32_e32 v12, v12, v13
	s_waitcnt lgkmcnt(0)
	v_add_f32_e32 v16, v16, v17
	ds_bpermute_b32 v11, v76, v10
	ds_bpermute_b32 v13, v76, v12
	ds_bpermute_b32 v17, v76, v16
	v_mov_b32_dpp v21, v19 quad_perm:[1,0,3,2] row_mask:0xf bank_mask:0xf
	v_cndmask_b32_e64 v19, v21, v90, s[6:7]
	s_waitcnt lgkmcnt(2)
	v_add_f32_e32 v10, v10, v11
	s_waitcnt lgkmcnt(1)
	v_add_f32_e32 v12, v12, v13
	s_waitcnt lgkmcnt(0)
	v_add_f32_e32 v16, v16, v17
	ds_bpermute_b32 v11, v77, v10
	ds_bpermute_b32 v13, v77, v12
	ds_bpermute_b32 v17, v77, v16
	v_cndmask_b32_e64 v21, v93, v21, s[6:7]
	global_store_dwordx4 v[80:81], v[18:21], off offset:1024 sc0 sc1
	s_waitcnt lgkmcnt(2)
	v_add_f32_e32 v10, v10, v11
	s_waitcnt lgkmcnt(1)
	v_add_f32_e32 v12, v12, v13
	s_waitcnt lgkmcnt(0)
	v_add_f32_e32 v22, v16, v17
	ds_bpermute_b32 v11, v78, v10
	ds_bpermute_b32 v13, v78, v12
	ds_bpermute_b32 v23, v78, v22
	s_waitcnt lgkmcnt(2)
	v_add_f32_e32 v16, v10, v11
	s_waitcnt lgkmcnt(1)
	v_add_f32_e32 v12, v12, v13
	s_waitcnt lgkmcnt(0)
	v_add_f32_e32 v10, v22, v23
	ds_bpermute_b32 v17, v79, v16
	ds_bpermute_b32 v13, v79, v12
	ds_bpermute_b32 v11, v79, v10
	s_and_saveexec_b64 s[38:39], s[4:5]
	s_cbranch_execnz .LBB0_48
	s_or_b64 exec, exec, s[38:39]
	s_andn2_b64 vcc, exec, s[30:31]
	s_cbranch_vccz .LBB0_49

.LBB0_49:
	v_cvt_pk_bf16_f32 v14, v38, v39
	v_cvt_pk_bf16_f32 v15, v40, v41
	v_cvt_pk_bf16_f32 v20, v42, v43
	v_cvt_pk_bf16_f32 v21, v44, v45
	s_ashr_i32 s1, s0, 31
	v_cndmask_b32_e64 v18, v14, v20, s[6:7]
	v_cndmask_b32_e64 v19, v15, v21, s[6:7]
	v_mov_b32_e32 v22, 0
	v_mov_b32_e32 v23, 0
	s_lshl_b64 s[12:13], s[0:1], 11
	v_mov_b32_dpp v22, v18 quad_perm:[1,0,3,2] row_mask:0xf bank_mask:0xf
	v_mov_b32_dpp v23, v19 quad_perm:[1,0,3,2] row_mask:0xf bank_mask:0xf
	v_cndmask_b32_e64 v18, v22, v14, s[6:7]
	v_cndmask_b32_e64 v19, v23, v15, s[6:7]
	v_cndmask_b32_e64 v20, v20, v22, s[6:7]
	v_cndmask_b32_e64 v21, v21, v23, s[6:7]
	v_lshl_add_u64 v[14:15], v[68:69], 0, s[12:13]
	global_store_dwordx4 v[14:15], v[18:21], off sc0 sc1
	v_mov_b32_e32 v24, 0
	s_nop 0
	v_cvt_pk_bf16_f32 v18, v34, v35
	v_cvt_pk_bf16_f32 v20, v62, v63
	v_cvt_pk_bf16_f32 v19, v36, v37
	v_cvt_pk_bf16_f32 v21, v64, v65
	v_cndmask_b32_e64 v22, v18, v20, s[6:7]
	v_cndmask_b32_e64 v23, v19, v21, s[6:7]
	s_nop 0
	v_mov_b32_dpp v24, v22 quad_perm:[1,0,3,2] row_mask:0xf bank_mask:0xf
	v_mov_b32_e32 v22, 0
	v_cndmask_b32_e64 v18, v24, v18, s[6:7]
	v_cndmask_b32_e64 v20, v20, v24, s[6:7]
	v_mov_b32_dpp v22, v23 quad_perm:[1,0,3,2] row_mask:0xf bank_mask:0xf
	v_cndmask_b32_e64 v19, v22, v19, s[6:7]
	v_cndmask_b32_e64 v21, v21, v22, s[6:7]
	global_store_dwordx4 v[14:15], v[18:21], off offset:1024 sc0 sc1
	s_and_saveexec_b64 s[12:13], s[4:5]
	s_cbranch_execz .LBB0_51
	s_waitcnt lgkmcnt(2)
	v_add_f32_e32 v16, v16, v17
	s_lshl_b64 s[20:21], s[0:1], 6
	v_lshl_add_u64 v[14:15], v[70:71], 0, s[20:21]
	v_cndmask_b32_e64 v16, 0, v16, s[8:9]
	global_store_dword v[14:15], v16, off

.LBB0_52:
	v_cvt_pk_bf16_f32 v14, v58, v59
	v_cvt_pk_bf16_f32 v16, v54, v55
	v_cvt_pk_bf16_f32 v15, v60, v61
	s_waitcnt lgkmcnt(2)
	v_cvt_pk_bf16_f32 v17, v56, v57
	v_cndmask_b32_e64 v18, v14, v16, s[6:7]
	v_mov_b32_e32 v20, 0
	s_ashr_i32 s17, s16, 31
	v_cndmask_b32_e64 v19, v15, v17, s[6:7]
	v_mov_b32_dpp v20, v18 quad_perm:[1,0,3,2] row_mask:0xf bank_mask:0xf
	v_mov_b32_e32 v18, 0
	s_lshl_b64 s[12:13], s[16:17], 11
	v_cndmask_b32_e64 v14, v20, v14, s[6:7]
	v_mov_b32_dpp v18, v19 quad_perm:[1,0,3,2] row_mask:0xf bank_mask:0xf
	v_cndmask_b32_e64 v15, v18, v15, s[6:7]
	v_cndmask_b32_e64 v16, v16, v20, s[6:7]
	v_cndmask_b32_e64 v17, v17, v18, s[6:7]
	v_lshl_add_u64 v[18:19], v[68:69], 0, s[12:13]
	global_store_dwordx4 v[18:19], v[14:17], off sc0 sc1
	v_mov_b32_e32 v22, 0
	s_nop 0
	v_cvt_pk_bf16_f32 v14, v50, v51
	v_cvt_pk_bf16_f32 v16, v46, v47
	v_cvt_pk_bf16_f32 v15, v52, v53
	v_cvt_pk_bf16_f32 v17, v48, v49
	v_cndmask_b32_e64 v20, v14, v16, s[6:7]
	v_cndmask_b32_e64 v21, v15, v17, s[6:7]
	s_nop 0
	v_mov_b32_dpp v22, v20 quad_perm:[1,0,3,2] row_mask:0xf bank_mask:0xf
	v_mov_b32_e32 v20, 0
	v_cndmask_b32_e64 v14, v22, v14, s[6:7]
	v_cndmask_b32_e64 v16, v16, v22, s[6:7]
	v_mov_b32_dpp v20, v21 quad_perm:[1,0,3,2] row_mask:0xf bank_mask:0xf
	v_cndmask_b32_e64 v15, v20, v15, s[6:7]
	v_cndmask_b32_e64 v17, v17, v20, s[6:7]
	global_store_dwordx4 v[18:19], v[14:17], off offset:1024 sc0 sc1
	s_and_saveexec_b64 s[12:13], s[4:5]
	s_cbranch_execz .LBB0_54
	s_waitcnt lgkmcnt(1)
	v_add_f32_e32 v14, v12, v13
	s_lshl_b64 s[16:17], s[16:17], 6
	v_lshl_add_u64 v[12:13], v[70:71], 0, s[16:17]
	v_cndmask_b32_e64 v14, 0, v14, s[8:9]
	global_store_dword v[12:13], v14, off

.LBB0_55:
	v_cvt_pk_bf16_f32 v12, v30, v31
	v_cvt_pk_bf16_f32 v14, v26, v27
	s_waitcnt lgkmcnt(1)
	v_cvt_pk_bf16_f32 v13, v32, v33
	v_cvt_pk_bf16_f32 v15, v28, v29
	v_cndmask_b32_e64 v16, v12, v14, s[6:7]
	v_mov_b32_e32 v18, 0
	v_cvt_pk_bf16_f32 v6, v6, v7
	v_cvt_pk_bf16_f32 v7, v8, v9
	v_cvt_pk_bf16_f32 v8, v2, v3
	v_cvt_pk_bf16_f32 v5, v4, v5
	s_ashr_i32 s15, s14, 31
	v_cndmask_b32_e64 v17, v13, v15, s[6:7]
	v_mov_b32_dpp v18, v16 quad_perm:[1,0,3,2] row_mask:0xf bank_mask:0xf
	v_mov_b32_e32 v16, 0
	v_cndmask_b32_e64 v2, v6, v8, s[6:7]
	v_cndmask_b32_e64 v3, v7, v5, s[6:7]
	v_mov_b32_e32 v4, 0
	v_mov_b32_e32 v9, 0
	s_lshl_b64 s[12:13], s[14:15], 11
	v_mov_b32_dpp v16, v17 quad_perm:[1,0,3,2] row_mask:0xf bank_mask:0xf
	v_mov_b32_dpp v4, v2 quad_perm:[1,0,3,2] row_mask:0xf bank_mask:0xf
	v_mov_b32_dpp v9, v3 quad_perm:[1,0,3,2] row_mask:0xf bank_mask:0xf
	v_cndmask_b32_e64 v12, v18, v12, s[6:7]
	v_cndmask_b32_e64 v13, v16, v13, s[6:7]
	v_cndmask_b32_e64 v14, v14, v18, s[6:7]
	v_cndmask_b32_e64 v15, v15, v16, s[6:7]
	v_lshl_add_u64 v[16:17], v[68:69], 0, s[12:13]
	v_cndmask_b32_e64 v2, v4, v6, s[6:7]
	v_cndmask_b32_e64 v3, v9, v7, s[6:7]
	v_cndmask_b32_e64 v4, v8, v4, s[6:7]
	v_cndmask_b32_e64 v5, v5, v9, s[6:7]
	global_store_dwordx4 v[16:17], v[12:15], off sc0 sc1
	global_store_dwordx4 v[16:17], v[2:5], off offset:1024 sc0 sc1
	s_and_saveexec_b64 s[12:13], s[4:5]
	s_cbranch_execz .LBB0_42
	s_waitcnt lgkmcnt(0)
	v_add_f32_e32 v4, v10, v11
	s_lshl_b64 s[14:15], s[14:15], 6
	v_lshl_add_u64 v[2:3], v[70:71], 0, s[14:15]
	v_cndmask_b32_e64 v4, 0, v4, s[8:9]
	global_store_dword v[2:3], v4, off
	s_branch .LBB0_42

.LBB0_146:
	s_waitcnt vmcnt(0)
	v_mul_f32_e32 v6, v6, v10
	ds_write2_b32 v1, v2, v6 offset0:48 offset1:56
	v_mul_f32_e32 v2, v7, v10
	ds_write2_b32 v1, v3, v2 offset0:114 offset1:122
	v_mul_f32_e32 v2, v8, v10
	ds_write2_b32 v1, v4, v2 offset0:180 offset1:188
	v_mul_f32_e32 v2, v9, v10
	ds_write2_b32 v1, v5, v2 offset0:246 offset1:254
	s_waitcnt lgkmcnt(0)
	v_add_u32_e32 v18, v54, v55
	ds_read2_b64 v[2:5], v18 offset1:1
	ds_read2_b64 v[6:9], v18 offset0:2 offset1:3
	s_mulk_i32 s10, 0xea00
	s_add_i32 s0, s22, s10
	s_and_b32 s0, s0, 0xffffff00
	s_and_b32 s1, s8, 0x60
	s_or_b32 s0, s1, s0
	s_waitcnt lgkmcnt(1)
	v_cvt_pk_bf16_f32 v2, v2, v3
	v_cvt_pk_bf16_f32 v3, v4, v5
	s_waitcnt lgkmcnt(0)
	v_cvt_pk_bf16_f32 v4, v6, v7
	v_or_b32_e32 v6, s0, v34
	v_ashrrev_i32_e32 v7, 31, v6
	v_lshlrev_b64 v[16:17], 11, v[6:7]
	v_add_u32_e32 v6, 0x840, v18
	v_cvt_pk_bf16_f32 v5, v8, v9
	ds_read2_b64 v[6:9], v6 offset1:1
	v_lshl_add_u64 v[14:15], s[6:7], 1, v[42:43]
	v_add_u32_e32 v10, 0x850, v18
	v_lshl_add_u64 v[16:17], v[14:15], 0, v[16:17]
	ds_read2_b64 v[10:13], v10 offset1:1
	global_store_dwordx4 v[16:17], v[2:5], off sc0 sc1
	s_waitcnt lgkmcnt(1)
	s_nop 0
	v_cvt_pk_bf16_f32 v2, v6, v7
	v_or_b32_e32 v6, s0, v56
	v_ashrrev_i32_e32 v7, 31, v6
	v_lshlrev_b64 v[16:17], 11, v[6:7]
	v_add_u32_e32 v6, 0x1080, v18
	v_cvt_pk_bf16_f32 v3, v8, v9
	ds_read2_b64 v[6:9], v6 offset1:1
	s_waitcnt lgkmcnt(1)
	v_cvt_pk_bf16_f32 v4, v10, v11
	v_cvt_pk_bf16_f32 v5, v12, v13
	v_add_u32_e32 v10, 0x1090, v18
	v_lshl_add_u64 v[16:17], v[14:15], 0, v[16:17]
	ds_read2_b64 v[10:13], v10 offset1:1
	global_store_dwordx4 v[16:17], v[2:5], off sc0 sc1
	s_waitcnt lgkmcnt(1)
	s_nop 0
	v_cvt_pk_bf16_f32 v2, v6, v7
	v_or_b32_e32 v6, s0, v57
	v_ashrrev_i32_e32 v7, 31, v6
	v_lshlrev_b64 v[16:17], 11, v[6:7]
	v_add_u32_e32 v6, 0x18c0, v18
	v_cvt_pk_bf16_f32 v3, v8, v9
	ds_read2_b64 v[6:9], v6 offset1:1
	s_waitcnt lgkmcnt(1)
	v_cvt_pk_bf16_f32 v4, v10, v11
	v_add_u32_e32 v10, 0x18d0, v18
	v_cvt_pk_bf16_f32 v5, v12, v13
	ds_read2_b64 v[10:13], v10 offset1:1
	v_lshl_add_u64 v[16:17], v[14:15], 0, v[16:17]
	global_store_dwordx4 v[16:17], v[2:5], off sc0 sc1
	s_waitcnt lgkmcnt(1)
	s_nop 0
	v_cvt_pk_bf16_f32 v2, v6, v7
	v_or_b32_e32 v6, s0, v58
	v_ashrrev_i32_e32 v7, 31, v6
	v_lshlrev_b64 v[6:7], 11, v[6:7]
	v_cvt_pk_bf16_f32 v3, v8, v9
	s_waitcnt lgkmcnt(0)
	v_cvt_pk_bf16_f32 v4, v10, v11
	v_cvt_pk_bf16_f32 v5, v12, v13
	v_lshl_add_u64 v[6:7], v[14:15], 0, v[6:7]
	global_store_dwordx4 v[6:7], v[2:5], off sc0 sc1
	s_waitcnt lgkmcnt(0)

.LBB0_169:
	s_lshl_b32 s10, s14, 1
	v_lshl_add_u64 v[10:11], v[38:39], 0, s[10:11]
	s_waitcnt lgkmcnt(1)
	v_cvt_pk_bf16_f32 v6, v6, v7
	v_cvt_pk_bf16_f32 v7, v8, v9
	s_waitcnt lgkmcnt(0)
	v_cvt_pk_bf16_f32 v8, v2, v3
	v_lshlrev_b64 v[2:3], 11, v[36:37]
	v_cvt_pk_bf16_f32 v9, v4, v5
	v_lshl_add_u64 v[2:3], v[10:11], 0, v[2:3]
	global_store_dwordx4 v[2:3], v[6:9], off sc0 sc1
	v_add_u32_e32 v2, 0x840, v12
	v_add_u32_e32 v3, 0x850, v12
	ds_read2_b64 v[6:9], v2 offset1:1
	ds_read2_b64 v[2:5], v3 offset1:1
	v_cndmask_b32_e64 v14, 0, 1, s[0:1]
	v_cmp_ne_u32_e64 s[8:9], 1, v14
	v_cndmask_b32_e64 v14, 0, 1, s[6:7]
	v_or_b32_e32 v13, s33, v56
	s_mov_b64 s[14:15], -1
	s_andn2_b64 vcc, exec, s[0:1]
	v_cmp_ne_u32_e64 s[6:7], 1, v14
	s_cbranch_vccnz .LBB0_177
	s_and_b64 vcc, exec, s[6:7]
	s_mov_b64 s[0:1], -1
	s_cbranch_vccnz .LBB0_174
	s_and_b32 s0, 0xffff, s18
	s_cmpk_lt_u32 s0, 0x68
	v_mov_b32_e32 v36, v13
	s_cbranch_scc1 .LBB0_173
	v_add_u32_e32 v14, 0xfffff300, v13
	v_lshlrev_b32_e32 v15, 1, v14
	v_lshrrev_b32_e32 v14, 3, v14
	v_and_b32_e32 v16, 0x6f, v13
	v_and_b32_e32 v14, 0x1fffff80, v14
	v_and_or_b32 v15, v15, s27, v16
	v_add3_u32 v36, v15, v14, s28

.LBB0_179:
	s_waitcnt lgkmcnt(0)
	v_cvt_pk_bf16_f32 v16, v2, v3
	v_lshlrev_b64 v[2:3], 11, v[36:37]
	v_lshl_add_u64 v[18:19], v[10:11], 0, v[2:3]
	v_add_u32_e32 v2, 0x1080, v12
	v_add_u32_e32 v3, 0x1090, v12
	v_cvt_pk_bf16_f32 v14, v6, v7
	v_cvt_pk_bf16_f32 v15, v8, v9
	v_cvt_pk_bf16_f32 v17, v4, v5
	ds_read2_b64 v[6:9], v2 offset1:1
	ds_read2_b64 v[2:5], v3 offset1:1
	v_or_b32_e32 v13, s33, v57
	s_and_b64 vcc, exec, s[8:9]
	s_mov_b64 s[0:1], -1
	global_store_dwordx4 v[18:19], v[14:17], off sc0 sc1
	s_cbranch_vccnz .LBB0_187
	s_and_b64 vcc, exec, s[6:7]
	s_cbranch_vccnz .LBB0_184
	s_and_b32 s0, 0xffff, s18
	s_cmpk_lt_u32 s0, 0x68
	v_mov_b32_e32 v36, v13
	s_cbranch_scc1 .LBB0_183
	v_add_u32_e32 v14, 0xfffff300, v13
	v_lshlrev_b32_e32 v15, 1, v14
	v_lshrrev_b32_e32 v14, 3, v14
	v_and_b32_e32 v16, 0x77, v13
	v_and_b32_e32 v14, 0x1fffff80, v14
	v_and_or_b32 v15, v15, s27, v16
	v_add3_u32 v36, v15, v14, s28

.LBB0_189:
	s_waitcnt lgkmcnt(0)
	v_cvt_pk_bf16_f32 v16, v2, v3
	v_lshlrev_b64 v[2:3], 11, v[36:37]
	v_lshl_add_u64 v[18:19], v[10:11], 0, v[2:3]
	v_add_u32_e32 v2, 0x18c0, v12
	v_add_u32_e32 v3, 0x18d0, v12
	v_cvt_pk_bf16_f32 v14, v6, v7
	v_cvt_pk_bf16_f32 v15, v8, v9
	v_cvt_pk_bf16_f32 v17, v4, v5
	ds_read2_b64 v[6:9], v2 offset1:1
	ds_read2_b64 v[2:5], v3 offset1:1
	v_or_b32_e32 v12, s33, v58
	s_and_b64 vcc, exec, s[8:9]
	s_mov_b64 s[0:1], -1
	global_store_dwordx4 v[18:19], v[14:17], off sc0 sc1
	s_cbranch_vccnz .LBB0_197
	s_and_b64 vcc, exec, s[6:7]
	s_cbranch_vccnz .LBB0_194
	s_and_b32 s0, 0xffff, s18
	s_cmpk_lt_u32 s0, 0x68
	v_mov_b32_e32 v36, v12
	s_cbranch_scc1 .LBB0_193
	v_add_u32_e32 v13, 0xfffff300, v12
	v_lshlrev_b32_e32 v14, 1, v13
	v_lshrrev_b32_e32 v13, 3, v13
	v_and_b32_e32 v15, 0x7f, v12
	v_and_b32_e32 v13, 0x1fffff80, v13
	v_and_or_b32 v14, v14, s27, v15
	v_add3_u32 v36, v14, v13, s28

.LBB0_199:
	s_waitcnt lgkmcnt(1)
	v_cvt_pk_bf16_f32 v6, v6, v7
	v_cvt_pk_bf16_f32 v7, v8, v9
	s_waitcnt lgkmcnt(0)
	v_cvt_pk_bf16_f32 v8, v2, v3
	v_lshlrev_b64 v[2:3], 11, v[36:37]
	v_cvt_pk_bf16_f32 v9, v4, v5
	v_lshl_add_u64 v[2:3], v[10:11], 0, v[2:3]
	global_store_dwordx4 v[2:3], v[6:9], off sc0 sc1
	s_waitcnt lgkmcnt(0)
	s_mov_b64 s[0:1], 0
.LBB0_200:
	s_and_b64 vcc, exec, s[0:1]
	s_cbranch_vccz .LBB0_202
	s_add_i32 s1, s20, 0xfffea000
	s_and_b32 s0, s24, 0xfc0
	s_and_b32 s1, s1, 0x3e0
	v_or_b32_e32 v4, s0, v34
	s_lshl_b32 s10, s1, 2
	v_lshl_add_u64 v[2:3], v[46:47], 0, s[10:11]
	v_lshlrev_b32_e32 v36, 12, v4
	v_lshl_add_u64 v[26:27], v[2:3], 0, v[36:37]
	v_add_co_u32_e32 v6, vcc, s29, v26
	v_add_u32_e32 v59, v54, v55
	s_nop 0
	v_addc_co_u32_e32 v7, vcc, 0, v27, vcc
	v_add_co_u32_e32 v10, vcc, s30, v26
	global_load_dwordx4 v[2:5], v[26:27], off
	s_nop 0
	global_load_dwordx4 v[6:9], v[6:7], off
	v_addc_co_u32_e32 v11, vcc, 0, v27, vcc
	v_add_co_u32_e32 v14, vcc, s31, v26
	v_or_b32_e32 v36, s1, v34
	s_nop 0
	v_addc_co_u32_e32 v15, vcc, 0, v27, vcc
	v_add_co_u32_e32 v18, vcc, s36, v26
	global_load_dwordx4 v[10:13], v[10:11], off
	s_nop 0
	global_load_dwordx4 v[14:17], v[14:15], off
	v_addc_co_u32_e32 v19, vcc, 0, v27, vcc
	v_add_co_u32_e32 v22, vcc, s37, v26
	v_add_u32_e32 v64, 0x840, v59
	s_nop 0
	v_addc_co_u32_e32 v23, vcc, 0, v27, vcc
	v_add_co_u32_e32 v28, vcc, s38, v26
	global_load_dwordx4 v[18:21], v[18:19], off
	s_nop 0
	global_load_dwordx4 v[22:25], v[22:23], off
	v_addc_co_u32_e32 v29, vcc, 0, v27, vcc
	v_add_co_u32_e32 v30, vcc, s39, v26
	v_add_u32_e32 v65, 0x850, v59
	s_nop 0
	v_addc_co_u32_e32 v31, vcc, 0, v27, vcc
	global_load_dwordx4 v[26:29], v[28:29], off
	s_nop 0
	global_load_dwordx4 v[30:33], v[30:31], off
	v_add_u32_e32 v66, 0x1080, v59
	v_add_u32_e32 v67, 0x1090, v59
	v_or_b32_e32 v52, s1, v56
	s_lshl_b32 s10, s0, 1
	v_mul_u32_u24_e32 v36, 0xb00, v36
	v_mul_u32_u24_e32 v62, 0xb00, v52
	v_lshl_add_u64 v[52:53], v[40:41], 0, s[10:11]
	v_lshlrev_b32_e32 v36, 1, v36
	v_lshl_add_u64 v[60:61], v[52:53], 0, v[36:37]
	v_lshlrev_b32_e32 v36, 1, v62
	v_lshl_add_u64 v[62:63], v[52:53], 0, v[36:37]
	s_waitcnt vmcnt(6)
	ds_write2_b32 v1, v2, v6 offset1:8
	ds_write2_b32 v1, v3, v7 offset0:66 offset1:74
	ds_write2_b32 v1, v4, v8 offset0:132 offset1:140
	ds_write2_b32 v1, v5, v9 offset0:198 offset1:206
	s_waitcnt vmcnt(4)
	ds_write2_b32 v1, v10, v14 offset0:16 offset1:24
	ds_write2_b32 v1, v11, v15 offset0:82 offset1:90
	ds_write2_b32 v1, v12, v16 offset0:148 offset1:156
	ds_write2_b32 v1, v13, v17 offset0:214 offset1:222
	s_waitcnt vmcnt(2)
	ds_write2_b32 v1, v18, v22 offset0:32 offset1:40
	ds_write2_b32 v1, v19, v23 offset0:98 offset1:106
	ds_write2_b32 v1, v20, v24 offset0:164 offset1:172
	ds_write2_b32 v1, v21, v25 offset0:230 offset1:238
	s_waitcnt vmcnt(0)
	ds_write2_b32 v1, v26, v30 offset0:48 offset1:56
	ds_write2_b32 v1, v27, v31 offset0:114 offset1:122
	ds_write2_b32 v1, v28, v32 offset0:180 offset1:188
	ds_write2_b32 v1, v29, v33 offset0:246 offset1:254
	s_waitcnt lgkmcnt(0)
	ds_read2_b64 v[2:5], v59 offset1:1
	ds_read2_b64 v[6:9], v59 offset0:2 offset1:3
	ds_read2_b64 v[10:13], v64 offset1:1
	ds_read2_b64 v[14:17], v65 offset1:1
	ds_read2_b64 v[18:21], v66 offset1:1
	ds_read2_b64 v[22:25], v67 offset1:1
	s_waitcnt lgkmcnt(5)
	v_cvt_pk_bf16_f32 v2, v2, v3
	v_cvt_pk_bf16_f32 v3, v4, v5
	s_waitcnt lgkmcnt(4)
	v_cvt_pk_bf16_f32 v4, v6, v7
	v_cvt_pk_bf16_f32 v5, v8, v9
	s_waitcnt lgkmcnt(3)
	v_cvt_pk_bf16_f32 v6, v10, v11
	v_cvt_pk_bf16_f32 v7, v12, v13
	s_waitcnt lgkmcnt(2)
	v_cvt_pk_bf16_f32 v8, v14, v15
	v_cvt_pk_bf16_f32 v9, v16, v17
	global_store_dwordx4 v[60:61], v[2:5], off sc0 sc1
	global_store_dwordx4 v[62:63], v[6:9], off sc0 sc1
	s_waitcnt lgkmcnt(1)
	v_cvt_pk_bf16_f32 v10, v18, v19
	v_or_b32_e32 v2, s1, v57
	v_mul_u32_u24_e32 v2, 0xb00, v2
	v_lshlrev_b32_e32 v36, 1, v2
	v_add_u32_e32 v2, 0x18c0, v59
	v_add_u32_e32 v6, 0x18d0, v59
	ds_read2_b64 v[2:5], v2 offset1:1
	ds_read2_b64 v[6:9], v6 offset1:1
	v_lshl_add_u64 v[14:15], v[52:53], 0, v[36:37]
	v_cvt_pk_bf16_f32 v11, v20, v21
	s_waitcnt lgkmcnt(2)
	v_cvt_pk_bf16_f32 v12, v22, v23
	s_waitcnt lgkmcnt(1)
	v_cvt_pk_bf16_f32 v2, v2, v3
	v_cvt_pk_bf16_f32 v3, v4, v5
	s_waitcnt lgkmcnt(0)
	v_cvt_pk_bf16_f32 v4, v6, v7
	v_or_b32_e32 v6, s1, v58
	v_mul_u32_u24_e32 v6, 0xb00, v6
	v_lshlrev_b32_e32 v36, 1, v6
	v_cvt_pk_bf16_f32 v13, v24, v25
	v_cvt_pk_bf16_f32 v5, v8, v9
	v_lshl_add_u64 v[6:7], v[52:53], 0, v[36:37]
	global_store_dwordx4 v[14:15], v[10:13], off sc0 sc1
	global_store_dwordx4 v[6:7], v[2:5], off sc0 sc1
	s_waitcnt lgkmcnt(0)

.LBB0_212:
	s_waitcnt vmcnt(0)
	v_mul_f32_e32 v6, v6, v18
	ds_write2_b32 v1, v2, v6 offset0:48 offset1:56
	v_mul_f32_e32 v2, v7, v18
	ds_write2_b32 v1, v3, v2 offset0:114 offset1:122
	v_mul_f32_e32 v2, v8, v18
	ds_write2_b32 v1, v4, v2 offset0:180 offset1:188
	v_mul_f32_e32 v2, v9, v18
	ds_write2_b32 v1, v5, v2 offset0:246 offset1:254
	s_waitcnt lgkmcnt(0)
	v_add_u32_e32 v18, v54, v55
	ds_read2_b64 v[2:5], v18 offset1:1
	ds_read2_b64 v[6:9], v18 offset0:2 offset1:3
	s_lshl_b32 s6, s1, 5
	s_lshl_b32 s1, s1, 6
	s_and_b32 s1, s1, 0x1f00
	s_and_b32 s6, s6, 0x60
	s_or_b32 s1, s1, s6
	s_bitset1_b32 s1, 7
	s_waitcnt lgkmcnt(1)
	v_cvt_pk_bf16_f32 v2, v2, v3
	v_cvt_pk_bf16_f32 v3, v4, v5
	s_waitcnt lgkmcnt(0)
	v_cvt_pk_bf16_f32 v4, v6, v7
	v_or_b32_e32 v6, s1, v34
	v_lshlrev_b32_e32 v36, 11, v6
	v_add_u32_e32 v6, 0x840, v18
	v_cvt_pk_bf16_f32 v5, v8, v9
	ds_read2_b64 v[6:9], v6 offset1:1
	s_lshl_b32 s10, s0, 1
	v_lshl_add_u64 v[14:15], v[42:43], 0, s[10:11]
	v_add_u32_e32 v10, 0x850, v18
	ds_read2_b64 v[10:13], v10 offset1:1
	v_lshl_add_u64 v[16:17], v[14:15], 0, v[36:37]
	global_store_dwordx4 v[16:17], v[2:5], off sc0 sc1
	s_waitcnt lgkmcnt(1)
	s_nop 0
	v_cvt_pk_bf16_f32 v2, v6, v7
	v_or_b32_e32 v6, s1, v56
	v_lshlrev_b32_e32 v36, 11, v6
	v_add_u32_e32 v6, 0x1080, v18
	v_cvt_pk_bf16_f32 v3, v8, v9
	ds_read2_b64 v[6:9], v6 offset1:1
	s_waitcnt lgkmcnt(1)
	v_cvt_pk_bf16_f32 v4, v10, v11
	v_add_u32_e32 v10, 0x1090, v18
	v_cvt_pk_bf16_f32 v5, v12, v13
	ds_read2_b64 v[10:13], v10 offset1:1
	v_lshl_add_u64 v[16:17], v[14:15], 0, v[36:37]
	global_store_dwordx4 v[16:17], v[2:5], off sc0 sc1
	s_waitcnt lgkmcnt(1)
	s_nop 0
	v_cvt_pk_bf16_f32 v2, v6, v7
	v_or_b32_e32 v6, s1, v57
	v_lshlrev_b32_e32 v36, 11, v6
	v_add_u32_e32 v6, 0x18c0, v18
	v_cvt_pk_bf16_f32 v3, v8, v9
	ds_read2_b64 v[6:9], v6 offset1:1
	s_waitcnt lgkmcnt(1)
	v_cvt_pk_bf16_f32 v4, v10, v11
	v_add_u32_e32 v10, 0x18d0, v18
	v_cvt_pk_bf16_f32 v5, v12, v13
	ds_read2_b64 v[10:13], v10 offset1:1
	v_lshl_add_u64 v[16:17], v[14:15], 0, v[36:37]
	global_store_dwordx4 v[16:17], v[2:5], off sc0 sc1
	s_waitcnt lgkmcnt(1)
	s_nop 0
	v_cvt_pk_bf16_f32 v2, v6, v7
	v_or_b32_e32 v6, s1, v58
	v_lshlrev_b32_e32 v36, 11, v6
	v_cvt_pk_bf16_f32 v3, v8, v9
	s_waitcnt lgkmcnt(0)
	v_cvt_pk_bf16_f32 v4, v10, v11
	v_cvt_pk_bf16_f32 v5, v12, v13
	v_lshl_add_u64 v[6:7], v[14:15], 0, v[36:37]
	global_store_dwordx4 v[6:7], v[2:5], off sc0 sc1
	s_waitcnt lgkmcnt(0)

.LBB0_285:
	v_lshl_add_u32 v131, s39, 10, v220
	ds_read2_b32 v[134:135], v131 offset1:16
	v_lshl_or_b32 v132, s93, 7, v219
	v_lshl_add_u32 v130, s38, 8, v1
	v_ashrrev_i32_e32 v133, 31, v132
	s_mov_b64 s[38:39], -1
	s_waitcnt lgkmcnt(0)
	v_pk_mul_f32 v[122:123], v[122:123], v[134:135] op_sel_hi:[1,0]
	v_pk_mul_f32 v[126:127], v[126:127], v[134:135] op_sel_hi:[1,0]
	v_mul_f32_e32 v136, 0xbfb8aa3b, v122
	v_mul_f32_e32 v137, 0xbfb8aa3b, v123
	v_exp_f32_e32 v136, v136
	v_exp_f32_e32 v137, v137
	v_pk_mul_f32 v[124:125], v[124:125], v[134:135] op_sel_hi:[1,0]
	v_pk_mul_f32 v[114:115], v[114:115], v[134:135] op_sel_hi:[1,0]
	v_add_f32_e32 v136, 1.0, v136
	v_add_f32_e32 v137, 1.0, v137
	v_rcp_f32_e32 v136, v136
	v_rcp_f32_e32 v137, v137
	v_pk_mul_f32 v[118:119], v[118:119], v[134:135] op_sel_hi:[1,0]
	v_pk_mul_f32 v[116:117], v[116:117], v[134:135] op_sel_hi:[1,0]
	v_pk_mul_f32 v[120:121], v[120:121], v[134:135] op_sel_hi:[1,0]
	v_pk_mul_f32 v[122:123], v[122:123], v[136:137]
	v_pk_mul_f32 v[128:129], v[128:129], v[134:135] op_sel_hi:[1,0]
	v_pk_mul_f32 v[122:123], v[126:127], v[122:123]
	v_mul_f32_e32 v126, 0xbfb8aa3b, v124
	v_mul_f32_e32 v127, 0xbfb8aa3b, v125
	v_exp_f32_e32 v126, v126
	v_exp_f32_e32 v127, v127
	s_andn2_b64 vcc, exec, s[4:5]
	v_add_f32_e32 v126, 1.0, v126
	v_add_f32_e32 v127, 1.0, v127
	v_rcp_f32_e32 v126, v126
	v_rcp_f32_e32 v127, v127
	s_nop 0
	v_pk_mul_f32 v[124:125], v[124:125], v[126:127]
	v_mul_f32_e32 v126, 0xbfb8aa3b, v114
	v_mul_f32_e32 v127, 0xbfb8aa3b, v115
	v_exp_f32_e32 v126, v126
	v_exp_f32_e32 v127, v127
	v_pk_mul_f32 v[124:125], v[128:129], v[124:125]
	v_add_f32_e32 v126, 1.0, v126
	v_add_f32_e32 v127, 1.0, v127
	v_rcp_f32_e32 v126, v126
	v_rcp_f32_e32 v127, v127
	s_nop 0
	v_pk_mul_f32 v[114:115], v[114:115], v[126:127]
	s_nop 0
	v_pk_mul_f32 v[114:115], v[118:119], v[114:115]
	v_mul_f32_e32 v118, 0xbfb8aa3b, v116
	v_mul_f32_e32 v119, 0xbfb8aa3b, v117
	v_exp_f32_e32 v118, v118
	v_exp_f32_e32 v119, v119
	v_add_f32_e32 v118, 1.0, v118
	v_add_f32_e32 v119, 1.0, v119
	v_rcp_f32_e32 v118, v118
	v_rcp_f32_e32 v119, v119
	s_nop 0
	v_pk_mul_f32 v[116:117], v[116:117], v[118:119]
	s_nop 0
	v_pk_mul_f32 v[116:117], v[120:121], v[116:117]
	v_cvt_pk_bf16_f32 v120, v114, v115
	v_mov_b64_e32 v[114:115], s[54:55]
	v_cvt_pk_bf16_f32 v118, v122, v123
	v_cvt_pk_bf16_f32 v121, v116, v117
	v_mad_i64_i32 v[122:123], s[18:19], v130, s67, v[114:115]
	v_lshlrev_b64 v[116:117], 1, v[132:133]
	v_cvt_pk_bf16_f32 v119, v124, v125
	v_lshl_add_u64 v[122:123], v[122:123], 0, v[116:117]
	global_store_dwordx4 v[122:123], v[118:121], off sc0 sc1
	s_nop 1
	v_mov_b32_e32 v118, v135
	v_pk_mul_f32 v[106:107], v[106:107], v[118:119] op_sel_hi:[1,0]
	s_nop 0
	v_mul_f32_e32 v119, 0xbfb8aa3b, v106
	v_exp_f32_e32 v119, v119
	s_nop 0
	v_add_f32_e32 v119, 1.0, v119
	v_rcp_f32_e32 v120, v119
	v_pk_mul_f32 v[110:111], v[110:111], v[118:119] op_sel_hi:[1,0]
	v_mul_f32_e32 v119, 0xbfb8aa3b, v107
	v_exp_f32_e32 v119, v119
	s_nop 0
	v_add_f32_e32 v119, 1.0, v119
	v_rcp_f32_e32 v121, v119
	v_pk_mul_f32 v[108:109], v[108:109], v[118:119] op_sel_hi:[1,0]
	v_pk_mul_f32 v[98:99], v[98:99], v[118:119] op_sel_hi:[1,0]
	v_pk_mul_f32 v[102:103], v[102:103], v[118:119] op_sel_hi:[1,0]
	v_pk_mul_f32 v[106:107], v[106:107], v[120:121]
	v_pk_mul_f32 v[112:113], v[112:113], v[118:119] op_sel_hi:[1,0]
	v_pk_mul_f32 v[106:107], v[110:111], v[106:107]
	v_mul_f32_e32 v110, 0xbfb8aa3b, v108
	v_mul_f32_e32 v111, 0xbfb8aa3b, v109
	v_exp_f32_e32 v110, v110
	v_exp_f32_e32 v111, v111
	v_pk_mul_f32 v[104:105], v[104:105], v[118:119] op_sel_hi:[1,0]
	v_add_f32_e32 v110, 1.0, v110
	v_add_f32_e32 v111, 1.0, v111
	v_rcp_f32_e32 v110, v110
	v_rcp_f32_e32 v111, v111
	s_nop 0
	v_pk_mul_f32 v[108:109], v[108:109], v[110:111]
	v_mul_f32_e32 v110, 0xbfb8aa3b, v98
	v_mul_f32_e32 v111, 0xbfb8aa3b, v99
	v_exp_f32_e32 v110, v110
	v_exp_f32_e32 v111, v111
	v_pk_mul_f32 v[108:109], v[112:113], v[108:109]
	v_add_f32_e32 v110, 1.0, v110
	v_add_f32_e32 v111, 1.0, v111
	v_rcp_f32_e32 v110, v110
	v_rcp_f32_e32 v111, v111
	s_nop 0
	v_pk_mul_f32 v[98:99], v[98:99], v[110:111]
	s_nop 0
	v_pk_mul_f32 v[102:103], v[102:103], v[98:99]
	v_pk_mul_f32 v[98:99], v[100:101], v[118:119] op_sel_hi:[1,0]
	v_or_b32_e32 v110, 16, v130
	v_mul_f32_e32 v100, 0xbfb8aa3b, v98
	v_mul_f32_e32 v101, 0xbfb8aa3b, v99
	v_exp_f32_e32 v100, v100
	v_exp_f32_e32 v101, v101
	v_add_f32_e32 v100, 1.0, v100
	v_add_f32_e32 v101, 1.0, v101
	v_rcp_f32_e32 v100, v100
	v_rcp_f32_e32 v101, v101
	s_nop 0
	v_pk_mul_f32 v[98:99], v[98:99], v[100:101]
	s_nop 0
	v_pk_mul_f32 v[104:105], v[104:105], v[98:99]
	v_cvt_pk_bf16_f32 v100, v102, v103
	v_mad_i64_i32 v[102:103], s[18:19], v110, s67, v[114:115]
	v_cvt_pk_bf16_f32 v98, v106, v107
	v_cvt_pk_bf16_f32 v99, v108, v109
	v_cvt_pk_bf16_f32 v101, v104, v105
	v_lshl_add_u64 v[102:103], v[102:103], 0, v[116:117]
	global_store_dwordx4 v[102:103], v[98:101], off sc0 sc1
	ds_read2_b32 v[98:99], v131 offset0:32 offset1:48
	s_waitcnt lgkmcnt(0)
	v_pk_mul_f32 v[90:91], v[90:91], v[98:99] op_sel_hi:[1,0]
	s_nop 0
	v_mul_f32_e32 v100, 0xbfb8aa3b, v90
	v_mul_f32_e32 v101, 0xbfb8aa3b, v91
	v_exp_f32_e32 v100, v100
	v_exp_f32_e32 v101, v101
	v_pk_mul_f32 v[94:95], v[94:95], v[98:99] op_sel_hi:[1,0]
	v_pk_mul_f32 v[92:93], v[92:93], v[98:99] op_sel_hi:[1,0]
	v_add_f32_e32 v100, 1.0, v100
	v_add_f32_e32 v101, 1.0, v101
	v_rcp_f32_e32 v100, v100
	v_rcp_f32_e32 v101, v101
	v_pk_mul_f32 v[82:83], v[82:83], v[98:99] op_sel_hi:[1,0]
	v_pk_mul_f32 v[86:87], v[86:87], v[98:99] op_sel_hi:[1,0]
	v_pk_mul_f32 v[96:97], v[96:97], v[98:99] op_sel_hi:[1,0]
	v_pk_mul_f32 v[90:91], v[90:91], v[100:101]
	v_pk_mul_f32 v[88:89], v[88:89], v[98:99] op_sel_hi:[1,0]
	v_pk_mul_f32 v[90:91], v[94:95], v[90:91]
	v_mul_f32_e32 v94, 0xbfb8aa3b, v92
	v_mul_f32_e32 v95, 0xbfb8aa3b, v93
	v_exp_f32_e32 v94, v94
	v_exp_f32_e32 v95, v95
	v_add_f32_e32 v94, 1.0, v94
	v_add_f32_e32 v95, 1.0, v95
	v_rcp_f32_e32 v94, v94
	v_rcp_f32_e32 v95, v95
	s_nop 0
	v_pk_mul_f32 v[92:93], v[92:93], v[94:95]
	v_mul_f32_e32 v94, 0xbfb8aa3b, v82
	v_mul_f32_e32 v95, 0xbfb8aa3b, v83
	v_exp_f32_e32 v94, v94
	v_exp_f32_e32 v95, v95
	v_pk_mul_f32 v[92:93], v[96:97], v[92:93]
	v_add_f32_e32 v94, 1.0, v94
	v_add_f32_e32 v95, 1.0, v95
	v_rcp_f32_e32 v94, v94
	v_rcp_f32_e32 v95, v95
	s_nop 0
	v_pk_mul_f32 v[82:83], v[82:83], v[94:95]
	s_nop 0
	v_pk_mul_f32 v[86:87], v[86:87], v[82:83]
	v_pk_mul_f32 v[82:83], v[84:85], v[98:99] op_sel_hi:[1,0]
	v_or_b32_e32 v94, 32, v130
	v_mul_f32_e32 v84, 0xbfb8aa3b, v82
	v_mul_f32_e32 v85, 0xbfb8aa3b, v83
	v_exp_f32_e32 v84, v84
	v_exp_f32_e32 v85, v85
	v_add_f32_e32 v84, 1.0, v84
	v_add_f32_e32 v85, 1.0, v85
	v_rcp_f32_e32 v84, v84
	v_rcp_f32_e32 v85, v85
	s_nop 0
	v_pk_mul_f32 v[82:83], v[82:83], v[84:85]
	s_nop 0
	v_pk_mul_f32 v[88:89], v[88:89], v[82:83]
	v_cvt_pk_bf16_f32 v84, v86, v87
	v_mad_i64_i32 v[86:87], s[18:19], v94, s67, v[114:115]
	v_cvt_pk_bf16_f32 v82, v90, v91
	v_cvt_pk_bf16_f32 v83, v92, v93
	v_cvt_pk_bf16_f32 v85, v88, v89
	v_lshl_add_u64 v[86:87], v[86:87], 0, v[116:117]
	global_store_dwordx4 v[86:87], v[82:85], off sc0 sc1
	s_nop 1
	v_mov_b32_e32 v82, v99
	v_pk_mul_f32 v[74:75], v[74:75], v[82:83] op_sel_hi:[1,0]
	s_nop 0
	v_mul_f32_e32 v83, 0xbfb8aa3b, v74
	v_exp_f32_e32 v83, v83
	s_nop 0
	v_add_f32_e32 v83, 1.0, v83
	v_rcp_f32_e32 v84, v83
	v_pk_mul_f32 v[78:79], v[78:79], v[82:83] op_sel_hi:[1,0]
	v_mul_f32_e32 v83, 0xbfb8aa3b, v75
	v_exp_f32_e32 v83, v83
	s_nop 0
	v_add_f32_e32 v83, 1.0, v83
	v_rcp_f32_e32 v85, v83
	v_pk_mul_f32 v[76:77], v[76:77], v[82:83] op_sel_hi:[1,0]
	v_pk_mul_f32 v[66:67], v[66:67], v[82:83] op_sel_hi:[1,0]
	v_pk_mul_f32 v[70:71], v[70:71], v[82:83] op_sel_hi:[1,0]
	v_pk_mul_f32 v[74:75], v[74:75], v[84:85]
	v_pk_mul_f32 v[80:81], v[80:81], v[82:83] op_sel_hi:[1,0]
	v_pk_mul_f32 v[74:75], v[78:79], v[74:75]
	v_mul_f32_e32 v78, 0xbfb8aa3b, v76
	v_mul_f32_e32 v79, 0xbfb8aa3b, v77
	v_exp_f32_e32 v78, v78
	v_exp_f32_e32 v79, v79
	v_pk_mul_f32 v[72:73], v[72:73], v[82:83] op_sel_hi:[1,0]
	v_add_f32_e32 v78, 1.0, v78
	v_add_f32_e32 v79, 1.0, v79
	v_rcp_f32_e32 v78, v78
	v_rcp_f32_e32 v79, v79
	s_nop 0
	v_pk_mul_f32 v[76:77], v[76:77], v[78:79]
	v_mul_f32_e32 v78, 0xbfb8aa3b, v66
	v_mul_f32_e32 v79, 0xbfb8aa3b, v67
	v_exp_f32_e32 v78, v78
	v_exp_f32_e32 v79, v79
	v_pk_mul_f32 v[76:77], v[80:81], v[76:77]
	v_add_f32_e32 v78, 1.0, v78
	v_add_f32_e32 v79, 1.0, v79
	v_rcp_f32_e32 v78, v78
	v_rcp_f32_e32 v79, v79
	s_nop 0
	v_pk_mul_f32 v[66:67], v[66:67], v[78:79]
	s_nop 0
	v_pk_mul_f32 v[70:71], v[70:71], v[66:67]
	v_pk_mul_f32 v[66:67], v[68:69], v[82:83] op_sel_hi:[1,0]
	v_or_b32_e32 v78, 48, v130
	v_mul_f32_e32 v68, 0xbfb8aa3b, v66
	v_mul_f32_e32 v69, 0xbfb8aa3b, v67
	v_exp_f32_e32 v68, v68
	v_exp_f32_e32 v69, v69
	v_add_f32_e32 v68, 1.0, v68
	v_add_f32_e32 v69, 1.0, v69
	v_rcp_f32_e32 v68, v68
	v_rcp_f32_e32 v69, v69
	s_nop 0
	v_pk_mul_f32 v[66:67], v[66:67], v[68:69]
	s_nop 0
	v_pk_mul_f32 v[72:73], v[72:73], v[66:67]
	v_cvt_pk_bf16_f32 v68, v70, v71
	v_mad_i64_i32 v[70:71], s[18:19], v78, s67, v[114:115]
	v_cvt_pk_bf16_f32 v66, v74, v75
	v_cvt_pk_bf16_f32 v67, v76, v77
	v_cvt_pk_bf16_f32 v69, v72, v73
	v_lshl_add_u64 v[70:71], v[70:71], 0, v[116:117]
	global_store_dwordx4 v[70:71], v[66:69], off sc0 sc1
	ds_read2_b32 v[66:67], v131 offset0:128 offset1:144
	v_add_u32_e32 v70, 0x80, v130
	s_waitcnt lgkmcnt(0)
	v_pk_mul_f32 v[58:59], v[58:59], v[66:67] op_sel_hi:[1,0]
	s_nop 0
	v_mul_f32_e32 v68, 0xbfb8aa3b, v58
	v_mul_f32_e32 v69, 0xbfb8aa3b, v59
	v_exp_f32_e32 v68, v68
	v_exp_f32_e32 v69, v69
	v_pk_mul_f32 v[62:63], v[62:63], v[66:67] op_sel_hi:[1,0]
	v_pk_mul_f32 v[60:61], v[60:61], v[66:67] op_sel_hi:[1,0]
	v_add_f32_e32 v68, 1.0, v68
	v_add_f32_e32 v69, 1.0, v69
	v_rcp_f32_e32 v68, v68
	v_rcp_f32_e32 v69, v69
	v_pk_mul_f32 v[50:51], v[50:51], v[66:67] op_sel_hi:[1,0]
	v_pk_mul_f32 v[54:55], v[54:55], v[66:67] op_sel_hi:[1,0]
	v_pk_mul_f32 v[64:65], v[64:65], v[66:67] op_sel_hi:[1,0]
	v_pk_mul_f32 v[58:59], v[58:59], v[68:69]
	v_pk_mul_f32 v[56:57], v[56:57], v[66:67] op_sel_hi:[1,0]
	v_pk_mul_f32 v[58:59], v[62:63], v[58:59]
	v_mul_f32_e32 v62, 0xbfb8aa3b, v60
	v_mul_f32_e32 v63, 0xbfb8aa3b, v61
	v_exp_f32_e32 v62, v62
	v_exp_f32_e32 v63, v63
	v_add_f32_e32 v62, 1.0, v62
	v_add_f32_e32 v63, 1.0, v63
	v_rcp_f32_e32 v62, v62
	v_rcp_f32_e32 v63, v63
	s_nop 0
	v_pk_mul_f32 v[60:61], v[60:61], v[62:63]
	v_mul_f32_e32 v62, 0xbfb8aa3b, v50
	v_mul_f32_e32 v63, 0xbfb8aa3b, v51
	v_exp_f32_e32 v62, v62
	v_exp_f32_e32 v63, v63
	v_pk_mul_f32 v[60:61], v[64:65], v[60:61]
	v_add_f32_e32 v62, 1.0, v62
	v_add_f32_e32 v63, 1.0, v63
	v_rcp_f32_e32 v62, v62
	v_rcp_f32_e32 v63, v63
	s_nop 0
	v_pk_mul_f32 v[50:51], v[50:51], v[62:63]
	s_nop 0
	v_pk_mul_f32 v[54:55], v[54:55], v[50:51]
	v_pk_mul_f32 v[50:51], v[52:53], v[66:67] op_sel_hi:[1,0]
	s_nop 0
	v_mul_f32_e32 v52, 0xbfb8aa3b, v50
	v_mul_f32_e32 v53, 0xbfb8aa3b, v51
	v_exp_f32_e32 v52, v52
	v_exp_f32_e32 v53, v53
	v_add_f32_e32 v52, 1.0, v52
	v_add_f32_e32 v53, 1.0, v53
	v_rcp_f32_e32 v52, v52
	v_rcp_f32_e32 v53, v53
	s_nop 0
	v_pk_mul_f32 v[50:51], v[50:51], v[52:53]
	s_nop 0
	v_pk_mul_f32 v[56:57], v[56:57], v[50:51]
	v_cvt_pk_bf16_f32 v52, v54, v55
	v_mad_i64_i32 v[54:55], s[18:19], v70, s67, v[114:115]
	v_cvt_pk_bf16_f32 v50, v58, v59
	v_cvt_pk_bf16_f32 v51, v60, v61
	v_cvt_pk_bf16_f32 v53, v56, v57
	v_lshl_add_u64 v[54:55], v[54:55], 0, v[116:117]
	global_store_dwordx4 v[54:55], v[50:53], off sc0 sc1
	s_nop 1
	v_mov_b32_e32 v50, v67
	v_pk_mul_f32 v[42:43], v[42:43], v[50:51] op_sel_hi:[1,0]
	s_nop 0
	v_mul_f32_e32 v51, 0xbfb8aa3b, v42
	v_exp_f32_e32 v51, v51
	s_nop 0
	v_add_f32_e32 v51, 1.0, v51
	v_rcp_f32_e32 v52, v51
	v_pk_mul_f32 v[46:47], v[46:47], v[50:51] op_sel_hi:[1,0]
	v_mul_f32_e32 v51, 0xbfb8aa3b, v43
	v_exp_f32_e32 v51, v51
	s_nop 0
	v_add_f32_e32 v51, 1.0, v51
	v_rcp_f32_e32 v53, v51
	v_pk_mul_f32 v[44:45], v[44:45], v[50:51] op_sel_hi:[1,0]
	v_pk_mul_f32 v[34:35], v[34:35], v[50:51] op_sel_hi:[1,0]
	v_pk_mul_f32 v[38:39], v[38:39], v[50:51] op_sel_hi:[1,0]
	v_pk_mul_f32 v[42:43], v[42:43], v[52:53]
	v_pk_mul_f32 v[48:49], v[48:49], v[50:51] op_sel_hi:[1,0]
	v_pk_mul_f32 v[42:43], v[46:47], v[42:43]
	v_mul_f32_e32 v46, 0xbfb8aa3b, v44
	v_mul_f32_e32 v47, 0xbfb8aa3b, v45
	v_exp_f32_e32 v46, v46
	v_exp_f32_e32 v47, v47
	v_pk_mul_f32 v[40:41], v[40:41], v[50:51] op_sel_hi:[1,0]
	v_add_f32_e32 v46, 1.0, v46
	v_add_f32_e32 v47, 1.0, v47
	v_rcp_f32_e32 v46, v46
	v_rcp_f32_e32 v47, v47
	s_nop 0
	v_pk_mul_f32 v[44:45], v[44:45], v[46:47]
	v_mul_f32_e32 v46, 0xbfb8aa3b, v34
	v_mul_f32_e32 v47, 0xbfb8aa3b, v35
	v_exp_f32_e32 v46, v46
	v_exp_f32_e32 v47, v47
	v_pk_mul_f32 v[44:45], v[48:49], v[44:45]
	v_add_f32_e32 v46, 1.0, v46
	v_add_f32_e32 v47, 1.0, v47
	v_rcp_f32_e32 v46, v46
	v_rcp_f32_e32 v47, v47
	s_nop 0
	v_pk_mul_f32 v[34:35], v[34:35], v[46:47]
	s_nop 0
	v_pk_mul_f32 v[38:39], v[38:39], v[34:35]
	v_pk_mul_f32 v[34:35], v[36:37], v[50:51] op_sel_hi:[1,0]
	v_add_u32_e32 v46, 0x90, v130
	v_mul_f32_e32 v36, 0xbfb8aa3b, v34
	v_mul_f32_e32 v37, 0xbfb8aa3b, v35
	v_exp_f32_e32 v36, v36
	v_exp_f32_e32 v37, v37
	v_add_f32_e32 v36, 1.0, v36
	v_add_f32_e32 v37, 1.0, v37
	v_rcp_f32_e32 v36, v36
	v_rcp_f32_e32 v37, v37
	s_nop 0
	v_pk_mul_f32 v[34:35], v[34:35], v[36:37]
	s_nop 0
	v_pk_mul_f32 v[40:41], v[40:41], v[34:35]
	v_cvt_pk_bf16_f32 v36, v38, v39
	v_mad_i64_i32 v[38:39], s[18:19], v46, s67, v[114:115]
	v_cvt_pk_bf16_f32 v34, v42, v43
	v_cvt_pk_bf16_f32 v35, v44, v45
	v_cvt_pk_bf16_f32 v37, v40, v41
	v_lshl_add_u64 v[38:39], v[38:39], 0, v[116:117]
	global_store_dwordx4 v[38:39], v[34:37], off sc0 sc1
	ds_read2_b32 v[34:35], v131 offset0:160 offset1:176
	s_waitcnt lgkmcnt(0)
	v_pk_mul_f32 v[26:27], v[26:27], v[34:35] op_sel_hi:[1,0]
	s_nop 0
	v_mul_f32_e32 v36, 0xbfb8aa3b, v26
	v_mul_f32_e32 v37, 0xbfb8aa3b, v27
	v_exp_f32_e32 v36, v36
	v_exp_f32_e32 v37, v37
	v_pk_mul_f32 v[30:31], v[30:31], v[34:35] op_sel_hi:[1,0]
	v_pk_mul_f32 v[28:29], v[28:29], v[34:35] op_sel_hi:[1,0]
	v_add_f32_e32 v36, 1.0, v36
	v_add_f32_e32 v37, 1.0, v37
	v_rcp_f32_e32 v36, v36
	v_rcp_f32_e32 v37, v37
	v_pk_mul_f32 v[18:19], v[18:19], v[34:35] op_sel_hi:[1,0]
	v_pk_mul_f32 v[22:23], v[22:23], v[34:35] op_sel_hi:[1,0]
	v_pk_mul_f32 v[32:33], v[32:33], v[34:35] op_sel_hi:[1,0]
	v_pk_mul_f32 v[26:27], v[26:27], v[36:37]
	v_pk_mul_f32 v[24:25], v[24:25], v[34:35] op_sel_hi:[1,0]
	v_pk_mul_f32 v[26:27], v[30:31], v[26:27]
	v_mul_f32_e32 v30, 0xbfb8aa3b, v28
	v_mul_f32_e32 v31, 0xbfb8aa3b, v29
	v_exp_f32_e32 v30, v30
	v_exp_f32_e32 v31, v31
	v_add_f32_e32 v30, 1.0, v30
	v_add_f32_e32 v31, 1.0, v31
	v_rcp_f32_e32 v30, v30
	v_rcp_f32_e32 v31, v31
	s_nop 0
	v_pk_mul_f32 v[28:29], v[28:29], v[30:31]
	v_mul_f32_e32 v30, 0xbfb8aa3b, v18
	v_mul_f32_e32 v31, 0xbfb8aa3b, v19
	v_exp_f32_e32 v30, v30
	v_exp_f32_e32 v31, v31
	v_pk_mul_f32 v[28:29], v[32:33], v[28:29]
	v_add_f32_e32 v30, 1.0, v30
	v_add_f32_e32 v31, 1.0, v31
	v_rcp_f32_e32 v30, v30
	v_rcp_f32_e32 v31, v31
	s_nop 0
	v_pk_mul_f32 v[18:19], v[18:19], v[30:31]
	s_nop 0
	v_pk_mul_f32 v[22:23], v[22:23], v[18:19]
	v_pk_mul_f32 v[18:19], v[20:21], v[34:35] op_sel_hi:[1,0]
	v_add_u32_e32 v30, 0xa0, v130
	v_mul_f32_e32 v20, 0xbfb8aa3b, v18
	v_mul_f32_e32 v21, 0xbfb8aa3b, v19
	v_exp_f32_e32 v20, v20
	v_exp_f32_e32 v21, v21
	v_add_f32_e32 v20, 1.0, v20
	v_add_f32_e32 v21, 1.0, v21
	v_rcp_f32_e32 v20, v20
	v_rcp_f32_e32 v21, v21
	s_nop 0
	v_pk_mul_f32 v[18:19], v[18:19], v[20:21]
	s_nop 0
	v_pk_mul_f32 v[24:25], v[24:25], v[18:19]
	v_cvt_pk_bf16_f32 v20, v22, v23
	v_mad_i64_i32 v[22:23], s[18:19], v30, s67, v[114:115]
	v_cvt_pk_bf16_f32 v18, v26, v27
	v_cvt_pk_bf16_f32 v19, v28, v29
	v_cvt_pk_bf16_f32 v21, v24, v25
	v_lshl_add_u64 v[22:23], v[22:23], 0, v[116:117]
	global_store_dwordx4 v[22:23], v[18:21], off sc0 sc1
	s_nop 1
	v_mov_b32_e32 v18, v35
	v_pk_mul_f32 v[10:11], v[10:11], v[18:19] op_sel_hi:[1,0]
	s_nop 0
	v_mul_f32_e32 v19, 0xbfb8aa3b, v10
	v_exp_f32_e32 v19, v19
	s_nop 0
	v_add_f32_e32 v19, 1.0, v19
	v_rcp_f32_e32 v20, v19
	v_pk_mul_f32 v[14:15], v[14:15], v[18:19] op_sel_hi:[1,0]
	v_mul_f32_e32 v19, 0xbfb8aa3b, v11
	v_exp_f32_e32 v19, v19
	s_nop 0
	v_add_f32_e32 v19, 1.0, v19
	v_rcp_f32_e32 v21, v19
	v_pk_mul_f32 v[12:13], v[12:13], v[18:19] op_sel_hi:[1,0]
	v_pk_mul_f32 v[2:3], v[2:3], v[18:19] op_sel_hi:[1,0]
	v_pk_mul_f32 v[6:7], v[6:7], v[18:19] op_sel_hi:[1,0]
	v_pk_mul_f32 v[10:11], v[10:11], v[20:21]
	v_pk_mul_f32 v[16:17], v[16:17], v[18:19] op_sel_hi:[1,0]
	v_pk_mul_f32 v[10:11], v[14:15], v[10:11]
	v_mul_f32_e32 v14, 0xbfb8aa3b, v12
	v_mul_f32_e32 v15, 0xbfb8aa3b, v13
	v_exp_f32_e32 v14, v14
	v_exp_f32_e32 v15, v15
	v_pk_mul_f32 v[8:9], v[8:9], v[18:19] op_sel_hi:[1,0]
	v_add_f32_e32 v14, 1.0, v14
	v_add_f32_e32 v15, 1.0, v15
	v_rcp_f32_e32 v14, v14
	v_rcp_f32_e32 v15, v15
	s_nop 0
	v_pk_mul_f32 v[12:13], v[12:13], v[14:15]
	v_mul_f32_e32 v14, 0xbfb8aa3b, v2
	v_mul_f32_e32 v15, 0xbfb8aa3b, v3
	v_exp_f32_e32 v14, v14
	v_exp_f32_e32 v15, v15
	v_pk_mul_f32 v[12:13], v[16:17], v[12:13]
	v_add_f32_e32 v14, 1.0, v14
	v_add_f32_e32 v15, 1.0, v15
	v_rcp_f32_e32 v14, v14
	v_rcp_f32_e32 v15, v15
	s_nop 0
	v_pk_mul_f32 v[2:3], v[2:3], v[14:15]
	s_nop 0
	v_pk_mul_f32 v[6:7], v[6:7], v[2:3]
	v_pk_mul_f32 v[2:3], v[4:5], v[18:19] op_sel_hi:[1,0]
	v_add_u32_e32 v14, 0xb0, v130
	v_mul_f32_e32 v4, 0xbfb8aa3b, v2
	v_mul_f32_e32 v5, 0xbfb8aa3b, v3
	v_exp_f32_e32 v4, v4
	v_exp_f32_e32 v5, v5
	v_add_f32_e32 v4, 1.0, v4
	v_add_f32_e32 v5, 1.0, v5
	v_rcp_f32_e32 v4, v4
	v_rcp_f32_e32 v5, v5
	s_nop 0
	v_pk_mul_f32 v[2:3], v[2:3], v[4:5]
	s_nop 0
	v_pk_mul_f32 v[8:9], v[8:9], v[2:3]
	v_cvt_pk_bf16_f32 v4, v6, v7
	v_mad_i64_i32 v[6:7], s[18:19], v14, s67, v[114:115]
	v_cvt_pk_bf16_f32 v2, v10, v11
	v_cvt_pk_bf16_f32 v3, v12, v13
	v_cvt_pk_bf16_f32 v5, v8, v9
	v_lshl_add_u64 v[6:7], v[6:7], 0, v[116:117]
	global_store_dwordx4 v[6:7], v[2:5], off sc0 sc1
	s_cbranch_vccnz .LBB0_266
	s_andn2_b64 vcc, exec, s[0:1]
	s_cbranch_vccnz .LBB0_265
	s_barrier
	s_branch .LBB0_265

.LBB0_402:
	s_andn2_b32 s21, s21, 63
	v_and_or_b32 v98, v1, 32, s21
	v_ashrrev_i32_e32 v163, 5, v98
	v_lshl_add_u32 v158, s22, 8, v163
	v_ashrrev_i32_e32 v159, 31, v158
	s_lshl_b32 s4, s20, 8
	v_lshlrev_b64 v[98:99], 11, v[158:159]
	s_ashr_i32 s5, s4, 31
	v_and_b32_e32 v170, 31, v1
	v_lshl_add_u64 v[168:169], s[88:89], 0, v[98:99]
	s_lshl_b64 s[6:7], s[4:5], 1
	v_lshl_add_u64 v[98:99], v[168:169], 0, s[6:7]
	v_lshlrev_b32_e32 v160, 4, v170
	v_mov_b32_e32 v161, 0
	v_lshl_add_u64 v[98:99], v[98:99], 0, v[160:161]
	s_mov_b32 s10, 0x8000
	v_add_co_u32_e32 v100, vcc, s10, v98
	s_mov_b32 s8, 0x10000
	s_nop 0
	v_addc_co_u32_e32 v101, vcc, 0, v99, vcc
	s_waitcnt vmcnt(0)
	s_barrier
	global_load_dwordx4 v[164:167], v[98:99], off
	global_load_dwordx4 v[154:157], v[100:101], off
	v_add_co_u32_e32 v100, vcc, s8, v98
	s_mov_b32 s9, 0x18000
	s_nop 0
	v_addc_co_u32_e32 v101, vcc, 0, v99, vcc
	v_add_co_u32_e32 v102, vcc, s9, v98
	s_mov_b32 s11, 0x20000
	s_nop 0
	v_addc_co_u32_e32 v103, vcc, 0, v99, vcc
	global_load_dwordx4 v[150:153], v[100:101], off
	global_load_dwordx4 v[146:149], v[102:103], off
	v_add_co_u32_e32 v100, vcc, s11, v98
	s_mov_b32 s12, 0x28000
	s_nop 0
	v_addc_co_u32_e32 v101, vcc, 0, v99, vcc
	v_add_co_u32_e32 v102, vcc, s12, v98
	s_mov_b32 s13, 0x30000
	s_nop 0
	v_addc_co_u32_e32 v103, vcc, 0, v99, vcc
	s_lshl_b32 s15, s23, 7
	global_load_dwordx4 v[142:145], v[100:101], off
	global_load_dwordx4 v[130:133], v[102:103], off
	v_add_co_u32_e32 v100, vcc, s13, v98
	s_add_i32 s15, s15, 0
	s_nop 0
	v_addc_co_u32_e32 v101, vcc, 0, v99, vcc
	s_mov_b32 s14, 0x38000
	v_add_u32_e32 v162, s15, v252
	s_movk_i32 s15, 0x410
	v_add_co_u32_e32 v98, vcc, s14, v98
	v_mul_lo_u32 v171, v225, s15
	s_nop 0
	v_addc_co_u32_e32 v99, vcc, 0, v99, vcc
	v_add_u32_e32 v162, v162, v171
	global_load_dwordx4 v[102:105], v[100:101], off
	s_nop 0
	global_load_dwordx4 v[98:101], v[98:99], off
	ds_write_b128 v162, v[2:5]
	ds_write_b128 v162, v[58:61] offset:64
	ds_write_b128 v162, v[74:77] offset:16640
	ds_write_b128 v162, v[78:81] offset:16704
	ds_write_b128 v162, v[82:85] offset:33280
	ds_write_b128 v162, v[86:89] offset:33344
	ds_write_b128 v162, v[90:93] offset:49920
	ds_write_b128 v162, v[94:97] offset:49984
	ds_write_b128 v162, v[106:109] offset:512
	ds_write_b128 v162, v[110:113] offset:576
	ds_write_b128 v162, v[114:117] offset:17152
	ds_write_b128 v162, v[118:121] offset:17216
	ds_write_b128 v162, v[122:125] offset:33792
	ds_write_b128 v162, v[126:129] offset:33856
	ds_write_b128 v162, v[134:137] offset:50432
	ds_write_b128 v162, v[138:141] offset:50496
	v_add_u32_e32 v106, 0x80, v158
	v_ashrrev_i32_e32 v107, 31, v106
	v_lshlrev_b64 v[2:3], 11, v[106:107]
	v_lshl_add_u64 v[108:109], s[88:89], 0, v[2:3]
	v_lshl_add_u64 v[2:3], v[108:109], 0, s[6:7]
	v_lshl_add_u64 v[2:3], v[2:3], 0, v[160:161]
	v_add_co_u32_e32 v4, vcc, s10, v2
	s_waitcnt vmcnt(0) lgkmcnt(0)
	s_nop 0
	v_addc_co_u32_e32 v5, vcc, 0, v3, vcc
	s_barrier
	global_load_dwordx4 v[94:97], v[2:3], off
	global_load_dwordx4 v[90:93], v[4:5], off
	v_add_co_u32_e32 v4, vcc, s8, v2
	v_lshlrev_b32_e32 v112, 5, v170
	s_nop 0
	v_addc_co_u32_e32 v5, vcc, 0, v3, vcc
	v_add_co_u32_e32 v58, vcc, s9, v2
	v_and_b32_e32 v113, 7, v1
	s_nop 0
	v_addc_co_u32_e32 v59, vcc, 0, v3, vcc
	global_load_dwordx4 v[86:89], v[4:5], off
	global_load_dwordx4 v[82:85], v[58:59], off
	v_add_co_u32_e32 v4, vcc, s11, v2
	v_bfe_u32 v126, v1, 3, 2
	s_nop 0
	v_addc_co_u32_e32 v5, vcc, 0, v3, vcc
	v_add_co_u32_e32 v58, vcc, s12, v2
	v_mul_lo_u32 v1, v163, s15
	s_nop 0
	v_addc_co_u32_e32 v59, vcc, 0, v3, vcc
	global_load_dwordx4 v[78:81], v[4:5], off
	global_load_dwordx4 v[74:77], v[58:59], off
	v_add_co_u32_e32 v4, vcc, s13, v2
	v_add3_u32 v1, 0, v112, v1
	s_nop 0
	v_addc_co_u32_e32 v5, vcc, 0, v3, vcc
	v_add_co_u32_e32 v2, vcc, s14, v2
	v_lshl_or_b32 v110, v170, 3, s4
	s_nop 0
	v_addc_co_u32_e32 v3, vcc, 0, v3, vcc
	global_load_dwordx4 v[58:61], v[4:5], off
	s_nop 0
	global_load_dwordx4 v[2:5], v[2:3], off
	v_mov_b32_e32 v111, s5
	v_cmp_eq_u32_e64 s[4:5], 0, v113
	ds_read_b128 v[112:115], v1
	ds_read_b128 v[116:119], v1 offset:16
	v_lshlrev_b32_e32 v120, 16, v164
	v_and_b32_e32 v121, 0xffff0000, v164
	v_lshlrev_b32_e32 v122, 16, v165
	v_and_b32_e32 v123, 0xffff0000, v165
	s_waitcnt lgkmcnt(1)
	v_pk_fma_f32 v[122:123], v[114:115], 0.5, v[122:123] op_sel_hi:[1,0,1]
	v_pk_fma_f32 v[112:113], v[112:113], 0.5, v[120:121] op_sel_hi:[1,0,1]
	v_lshlrev_b32_e32 v114, 16, v166
	v_and_b32_e32 v115, 0xffff0000, v166
	v_lshlrev_b32_e32 v120, 16, v167
	v_and_b32_e32 v121, 0xffff0000, v167
	s_waitcnt lgkmcnt(0)
	v_pk_fma_f32 v[124:125], v[116:117], 0.5, v[114:115] op_sel_hi:[1,0,1]
	v_cvt_pk_bf16_f32 v116, v112, v113
	v_mul_f32_e32 v113, v113, v113
	v_pk_fma_f32 v[120:121], v[118:119], 0.5, v[120:121] op_sel_hi:[1,0,1]
	v_fmac_f32_e32 v113, v112, v112
	v_mul_f32_e32 v112, v123, v123
	v_cvt_pk_bf16_f32 v117, v122, v123
	v_cvt_pk_bf16_f32 v118, v124, v125
	v_cvt_pk_bf16_f32 v119, v120, v121
	v_lshl_add_u64 v[114:115], v[110:111], 1, v[168:169]
	v_fmac_f32_e32 v112, v122, v122
	global_store_dwordx4 v[114:115], v[116:119], off sc0 sc1
	v_add_f32_e32 v112, v113, v112
	v_mul_f32_e32 v113, v125, v125
	v_mul_f32_e32 v116, v121, v121
	v_fmac_f32_e32 v113, v124, v124
	v_fmac_f32_e32 v116, v120, v120
	v_add_f32_e32 v113, v113, v116
	v_add_f32_e32 v112, v112, v113
	s_lshl_b32 s6, s20, 2
	v_mov_b32_e32 v117, 0
	v_add_f32_dpp v112, v112, v112 quad_perm:[1,0,3,2] row_mask:0xf bank_mask:0xf bound_ctrl:1
	s_ashr_i32 s7, s6, 31
	v_lshlrev_b32_e32 v160, 2, v126
	v_add_f32_dpp v116, v112, v112 quad_perm:[2,3,0,1] row_mask:0xf bank_mask:0xf bound_ctrl:1
	v_lshlrev_b64 v[112:113], 6, v[158:159]
	s_nop 0
	v_mov_b32_dpp v117, v116 row_half_mirror row_mask:0xf bank_mask:0xf
	s_and_saveexec_b64 s[8:9], s[4:5]
	s_cbranch_execz .LBB0_404
	v_add_f32_e32 v118, v116, v117
	v_lshl_add_u64 v[116:117], s[0:1], 0, v[112:113]
	v_lshl_add_u64 v[116:117], s[6:7], 2, v[116:117]
	v_lshl_add_u64 v[116:117], v[116:117], 0, v[160:161]
	global_store_dword v[116:117], v118, off
.LBB0_404:
	s_or_b64 exec, exec, s[8:9]
	ds_read_b128 v[116:119], v1 offset:16640
	ds_read_b128 v[120:123], v1 offset:16656
	v_lshlrev_b32_e32 v124, 16, v154
	v_and_b32_e32 v125, 0xffff0000, v154
	v_lshlrev_b32_e32 v126, 16, v155
	v_and_b32_e32 v127, 0xffff0000, v155
	s_waitcnt lgkmcnt(1)
	v_pk_fma_f32 v[126:127], v[118:119], 0.5, v[126:127] op_sel_hi:[1,0,1]
	v_pk_fma_f32 v[124:125], v[116:117], 0.5, v[124:125] op_sel_hi:[1,0,1]
	v_lshlrev_b32_e32 v116, 16, v156
	v_and_b32_e32 v117, 0xffff0000, v156
	v_lshlrev_b32_e32 v118, 16, v157
	v_and_b32_e32 v119, 0xffff0000, v157
	s_waitcnt lgkmcnt(0)
	v_pk_fma_f32 v[122:123], v[122:123], 0.5, v[118:119] op_sel_hi:[1,0,1]
	v_pk_fma_f32 v[120:121], v[120:121], 0.5, v[116:117] op_sel_hi:[1,0,1]
	v_add_co_u32_e32 v128, vcc, s10, v114
	v_cvt_pk_bf16_f32 v116, v124, v125
	v_cvt_pk_bf16_f32 v117, v126, v127
	v_cvt_pk_bf16_f32 v118, v120, v121
	v_cvt_pk_bf16_f32 v119, v122, v123
	v_addc_co_u32_e32 v129, vcc, 0, v115, vcc
	global_store_dwordx4 v[128:129], v[116:119], off sc0 sc1
	s_nop 1
	v_mul_f32_e32 v116, v125, v125
	v_mul_f32_e32 v117, v127, v127
	v_fmac_f32_e32 v116, v124, v124
	v_fmac_f32_e32 v117, v126, v126
	v_add_f32_e32 v116, v116, v117
	v_mul_f32_e32 v117, v121, v121
	v_mul_f32_e32 v118, v123, v123
	v_fmac_f32_e32 v117, v120, v120
	v_fmac_f32_e32 v118, v122, v122
	v_add_f32_e32 v117, v117, v118
	v_add_f32_e32 v116, v116, v117
	s_nop 1
	v_add_f32_dpp v116, v116, v116 quad_perm:[1,0,3,2] row_mask:0xf bank_mask:0xf bound_ctrl:1
	s_nop 1
	v_add_f32_dpp v116, v116, v116 quad_perm:[2,3,0,1] row_mask:0xf bank_mask:0xf bound_ctrl:1
	s_nop 1
	v_mov_b32_dpp v161, v116 row_half_mirror row_mask:0xf bank_mask:0xf
	s_and_saveexec_b64 s[8:9], s[4:5]
	s_mov_b32 s92, s90
	s_mov_b32 s90, s95
	s_cbranch_execz .LBB0_406
	v_add_f32_e32 v118, v116, v161
	v_lshl_add_u64 v[116:117], s[0:1], 0, v[112:113]
	v_lshl_add_u64 v[116:117], s[6:7], 2, v[116:117]
	v_mov_b32_e32 v161, 0
	v_lshl_add_u64 v[116:117], v[116:117], 0, v[160:161]
	global_store_dword v[116:117], v118, off offset:1024
.LBB0_406:
	s_or_b64 exec, exec, s[8:9]
	ds_read_b128 v[116:119], v1 offset:33280
	ds_read_b128 v[120:123], v1 offset:33296
	v_lshlrev_b32_e32 v124, 16, v150
	v_and_b32_e32 v125, 0xffff0000, v150
	v_lshlrev_b32_e32 v126, 16, v151
	v_and_b32_e32 v127, 0xffff0000, v151
	s_waitcnt lgkmcnt(1)
	v_pk_fma_f32 v[126:127], v[118:119], 0.5, v[126:127] op_sel_hi:[1,0,1]
	v_pk_fma_f32 v[124:125], v[116:117], 0.5, v[124:125] op_sel_hi:[1,0,1]
	v_lshlrev_b32_e32 v116, 16, v152
	v_and_b32_e32 v117, 0xffff0000, v152
	v_lshlrev_b32_e32 v118, 16, v153
	v_and_b32_e32 v119, 0xffff0000, v153
	s_mov_b32 s8, 0x10000
	s_waitcnt lgkmcnt(0)
	v_pk_fma_f32 v[122:123], v[122:123], 0.5, v[118:119] op_sel_hi:[1,0,1]
	v_pk_fma_f32 v[120:121], v[120:121], 0.5, v[116:117] op_sel_hi:[1,0,1]
	v_add_co_u32_e32 v128, vcc, s8, v114
	v_cvt_pk_bf16_f32 v116, v124, v125
	v_cvt_pk_bf16_f32 v117, v126, v127
	v_cvt_pk_bf16_f32 v118, v120, v121
	v_cvt_pk_bf16_f32 v119, v122, v123
	v_addc_co_u32_e32 v129, vcc, 0, v115, vcc
	global_store_dwordx4 v[128:129], v[116:119], off sc0 sc1
	v_mov_b32_e32 v161, 0
	s_nop 0
	v_mul_f32_e32 v116, v125, v125
	v_mul_f32_e32 v117, v127, v127
	v_fmac_f32_e32 v116, v124, v124
	v_fmac_f32_e32 v117, v126, v126
	v_add_f32_e32 v116, v116, v117
	v_mul_f32_e32 v117, v121, v121
	v_mul_f32_e32 v118, v123, v123
	v_fmac_f32_e32 v117, v120, v120
	v_fmac_f32_e32 v118, v122, v122
	v_add_f32_e32 v117, v117, v118
	v_add_f32_e32 v116, v116, v117
	v_mov_b32_e32 v117, 0
	s_nop 0
	v_add_f32_dpp v116, v116, v116 quad_perm:[1,0,3,2] row_mask:0xf bank_mask:0xf bound_ctrl:1
	s_nop 1
	v_add_f32_dpp v116, v116, v116 quad_perm:[2,3,0,1] row_mask:0xf bank_mask:0xf bound_ctrl:1
	s_nop 1
	v_mov_b32_dpp v117, v116 row_half_mirror row_mask:0xf bank_mask:0xf
	s_and_saveexec_b64 s[8:9], s[4:5]
	s_cbranch_execz .LBB0_408
	v_add_f32_e32 v118, v116, v117
	v_lshl_add_u64 v[116:117], s[0:1], 0, v[112:113]
	v_lshl_add_u64 v[116:117], s[6:7], 2, v[116:117]
	v_lshl_add_u64 v[116:117], v[116:117], 0, v[160:161]
	global_store_dword v[116:117], v118, off offset:2048
.LBB0_408:
	s_or_b64 exec, exec, s[8:9]
	ds_read_b128 v[116:119], v1 offset:49920
	ds_read_b128 v[120:123], v1 offset:49936
	v_lshlrev_b32_e32 v124, 16, v146
	v_and_b32_e32 v125, 0xffff0000, v146
	v_lshlrev_b32_e32 v126, 16, v147
	v_and_b32_e32 v127, 0xffff0000, v147
	s_waitcnt lgkmcnt(1)
	v_pk_fma_f32 v[126:127], v[118:119], 0.5, v[126:127] op_sel_hi:[1,0,1]
	v_pk_fma_f32 v[124:125], v[116:117], 0.5, v[124:125] op_sel_hi:[1,0,1]
	v_lshlrev_b32_e32 v116, 16, v148
	v_and_b32_e32 v117, 0xffff0000, v148
	v_lshlrev_b32_e32 v118, 16, v149
	v_and_b32_e32 v119, 0xffff0000, v149
	s_mov_b32 s8, 0x18000
	s_waitcnt lgkmcnt(0)
	v_pk_fma_f32 v[122:123], v[122:123], 0.5, v[118:119] op_sel_hi:[1,0,1]
	v_pk_fma_f32 v[120:121], v[120:121], 0.5, v[116:117] op_sel_hi:[1,0,1]
	v_add_co_u32_e32 v128, vcc, s8, v114
	v_cvt_pk_bf16_f32 v116, v124, v125
	v_cvt_pk_bf16_f32 v117, v126, v127
	v_cvt_pk_bf16_f32 v118, v120, v121
	v_cvt_pk_bf16_f32 v119, v122, v123
	v_addc_co_u32_e32 v129, vcc, 0, v115, vcc
	global_store_dwordx4 v[128:129], v[116:119], off sc0 sc1
	s_nop 1
	v_mul_f32_e32 v116, v125, v125
	v_mul_f32_e32 v117, v127, v127
	v_fmac_f32_e32 v116, v124, v124
	v_fmac_f32_e32 v117, v126, v126
	v_add_f32_e32 v116, v116, v117
	v_mul_f32_e32 v117, v121, v121
	v_mul_f32_e32 v118, v123, v123
	v_fmac_f32_e32 v117, v120, v120
	v_fmac_f32_e32 v118, v122, v122
	v_add_f32_e32 v117, v117, v118
	v_add_f32_e32 v116, v116, v117
	s_nop 1
	v_add_f32_dpp v116, v116, v116 quad_perm:[1,0,3,2] row_mask:0xf bank_mask:0xf bound_ctrl:1
	s_nop 1
	v_add_f32_dpp v116, v116, v116 quad_perm:[2,3,0,1] row_mask:0xf bank_mask:0xf bound_ctrl:1
	s_nop 1
	v_mov_b32_dpp v161, v116 row_half_mirror row_mask:0xf bank_mask:0xf
	s_and_saveexec_b64 s[8:9], s[4:5]
	s_cbranch_execz .LBB0_410
	v_add_f32_e32 v118, v116, v161
	v_lshl_add_u64 v[116:117], s[0:1], 0, v[112:113]
	v_lshl_add_u64 v[116:117], s[6:7], 2, v[116:117]
	v_mov_b32_e32 v161, 0
	v_lshl_add_u64 v[116:117], v[116:117], 0, v[160:161]
	global_store_dword v[116:117], v118, off offset:3072
.LBB0_410:
	s_or_b64 exec, exec, s[8:9]
	v_add_u32_e32 v116, 0x10400, v1
	v_add_u32_e32 v117, 0x10410, v1
	ds_read_b128 v[118:121], v116
	ds_read_b128 v[122:125], v117
	v_lshlrev_b32_e32 v126, 16, v142
	v_and_b32_e32 v127, 0xffff0000, v142
	v_lshlrev_b32_e32 v128, 16, v143
	v_and_b32_e32 v129, 0xffff0000, v143
	s_waitcnt lgkmcnt(1)
	v_pk_fma_f32 v[128:129], v[120:121], 0.5, v[128:129] op_sel_hi:[1,0,1]
	v_pk_fma_f32 v[126:127], v[118:119], 0.5, v[126:127] op_sel_hi:[1,0,1]
	v_lshlrev_b32_e32 v118, 16, v144
	v_and_b32_e32 v119, 0xffff0000, v144
	v_lshlrev_b32_e32 v120, 16, v145
	v_and_b32_e32 v121, 0xffff0000, v145
	s_mov_b32 s8, 0x20000
	s_waitcnt lgkmcnt(0)
	v_pk_fma_f32 v[124:125], v[124:125], 0.5, v[120:121] op_sel_hi:[1,0,1]
	v_pk_fma_f32 v[122:123], v[122:123], 0.5, v[118:119] op_sel_hi:[1,0,1]
	v_add_co_u32_e32 v134, vcc, s8, v114
	v_cvt_pk_bf16_f32 v118, v126, v127
	v_cvt_pk_bf16_f32 v119, v128, v129
	v_cvt_pk_bf16_f32 v120, v122, v123
	v_cvt_pk_bf16_f32 v121, v124, v125
	v_addc_co_u32_e32 v135, vcc, 0, v115, vcc
	global_store_dwordx4 v[134:135], v[118:121], off sc0 sc1
	v_mov_b32_e32 v161, 0
	s_nop 0
	v_mul_f32_e32 v118, v127, v127
	v_mul_f32_e32 v119, v129, v129
	v_fmac_f32_e32 v118, v126, v126
	v_fmac_f32_e32 v119, v128, v128
	v_add_f32_e32 v118, v118, v119
	v_mul_f32_e32 v119, v123, v123
	v_mul_f32_e32 v120, v125, v125
	v_fmac_f32_e32 v119, v122, v122
	v_fmac_f32_e32 v120, v124, v124
	v_add_f32_e32 v119, v119, v120
	v_add_f32_e32 v118, v118, v119
	v_mov_b32_e32 v119, 0
	s_nop 0
	v_add_f32_dpp v118, v118, v118 quad_perm:[1,0,3,2] row_mask:0xf bank_mask:0xf bound_ctrl:1
	s_nop 1
	v_add_f32_dpp v118, v118, v118 quad_perm:[2,3,0,1] row_mask:0xf bank_mask:0xf bound_ctrl:1
	s_nop 1
	v_mov_b32_dpp v119, v118 row_half_mirror row_mask:0xf bank_mask:0xf
	s_and_saveexec_b64 s[8:9], s[4:5]
	s_cbranch_execz .LBB0_412
	v_add_f32_e32 v120, v118, v119
	v_lshl_add_u64 v[118:119], s[0:1], 0, v[112:113]
	v_lshl_add_u64 v[118:119], s[6:7], 2, v[118:119]
	v_lshl_add_u64 v[118:119], v[118:119], 0, v[160:161]
	v_add_co_u32_e32 v118, vcc, 0x1000, v118
	s_nop 1
	v_addc_co_u32_e32 v119, vcc, 0, v119, vcc
	global_store_dword v[118:119], v120, off
.LBB0_412:
	s_or_b64 exec, exec, s[8:9]
	v_add_u32_e32 v118, 0x14500, v1
	v_add_u32_e32 v119, 0x14510, v1
	ds_read_b128 v[120:123], v118
	ds_read_b128 v[124:127], v119
	v_lshlrev_b32_e32 v128, 16, v130
	v_and_b32_e32 v129, 0xffff0000, v130
	v_lshlrev_b32_e32 v130, 16, v131
	v_and_b32_e32 v131, 0xffff0000, v131
	s_waitcnt lgkmcnt(1)
	v_pk_fma_f32 v[130:131], v[122:123], 0.5, v[130:131] op_sel_hi:[1,0,1]
	v_pk_fma_f32 v[128:129], v[120:121], 0.5, v[128:129] op_sel_hi:[1,0,1]
	v_lshlrev_b32_e32 v120, 16, v132
	v_and_b32_e32 v121, 0xffff0000, v132
	v_lshlrev_b32_e32 v122, 16, v133
	v_and_b32_e32 v123, 0xffff0000, v133
	s_mov_b32 s8, 0x28000
	s_waitcnt lgkmcnt(0)
	v_pk_fma_f32 v[126:127], v[126:127], 0.5, v[122:123] op_sel_hi:[1,0,1]
	v_pk_fma_f32 v[124:125], v[124:125], 0.5, v[120:121] op_sel_hi:[1,0,1]
	v_add_co_u32_e32 v132, vcc, s8, v114
	v_cvt_pk_bf16_f32 v120, v128, v129
	v_cvt_pk_bf16_f32 v121, v130, v131
	v_cvt_pk_bf16_f32 v122, v124, v125
	v_cvt_pk_bf16_f32 v123, v126, v127
	v_addc_co_u32_e32 v133, vcc, 0, v115, vcc
	global_store_dwordx4 v[132:133], v[120:123], off sc0 sc1
	s_nop 1
	v_mul_f32_e32 v120, v129, v129
	v_mul_f32_e32 v121, v131, v131
	v_fmac_f32_e32 v120, v128, v128
	v_fmac_f32_e32 v121, v130, v130
	v_add_f32_e32 v120, v120, v121
	v_mul_f32_e32 v121, v125, v125
	v_mul_f32_e32 v122, v127, v127
	v_fmac_f32_e32 v121, v124, v124
	v_fmac_f32_e32 v122, v126, v126
	v_add_f32_e32 v121, v121, v122
	v_add_f32_e32 v120, v120, v121
	s_nop 1
	v_add_f32_dpp v120, v120, v120 quad_perm:[1,0,3,2] row_mask:0xf bank_mask:0xf bound_ctrl:1
	s_nop 1
	v_add_f32_dpp v120, v120, v120 quad_perm:[2,3,0,1] row_mask:0xf bank_mask:0xf bound_ctrl:1
	s_nop 1
	v_mov_b32_dpp v161, v120 row_half_mirror row_mask:0xf bank_mask:0xf
	s_and_saveexec_b64 s[8:9], s[4:5]
	s_cbranch_execz .LBB0_414
	v_add_f32_e32 v122, v120, v161
	v_lshl_add_u64 v[120:121], s[0:1], 0, v[112:113]
	v_lshl_add_u64 v[120:121], s[6:7], 2, v[120:121]
	v_mov_b32_e32 v161, 0
	v_lshl_add_u64 v[120:121], v[120:121], 0, v[160:161]
	v_add_co_u32_e32 v120, vcc, 0x1000, v120
	s_nop 1
	v_addc_co_u32_e32 v121, vcc, 0, v121, vcc
	global_store_dword v[120:121], v122, off offset:1024
.LBB0_414:
	s_or_b64 exec, exec, s[8:9]
	v_add_u32_e32 v120, 0x18600, v1
	v_add_u32_e32 v121, 0x18610, v1
	ds_read_b128 v[122:125], v120
	ds_read_b128 v[126:129], v121
	v_lshlrev_b32_e32 v130, 16, v102
	v_and_b32_e32 v131, 0xffff0000, v102
	v_lshlrev_b32_e32 v102, 16, v103
	v_and_b32_e32 v103, 0xffff0000, v103
	s_waitcnt lgkmcnt(1)
	v_pk_fma_f32 v[124:125], v[124:125], 0.5, v[102:103] op_sel_hi:[1,0,1]
	v_lshlrev_b32_e32 v102, 16, v104
	v_and_b32_e32 v103, 0xffff0000, v104
	v_lshlrev_b32_e32 v104, 16, v105
	v_and_b32_e32 v105, 0xffff0000, v105
	s_mov_b32 s8, 0x30000
	v_pk_fma_f32 v[122:123], v[122:123], 0.5, v[130:131] op_sel_hi:[1,0,1]
	s_waitcnt lgkmcnt(0)
	v_pk_fma_f32 v[128:129], v[128:129], 0.5, v[104:105] op_sel_hi:[1,0,1]
	v_pk_fma_f32 v[126:127], v[126:127], 0.5, v[102:103] op_sel_hi:[1,0,1]
	v_add_co_u32_e32 v130, vcc, s8, v114
	v_cvt_pk_bf16_f32 v102, v122, v123
	v_cvt_pk_bf16_f32 v103, v124, v125
	v_cvt_pk_bf16_f32 v104, v126, v127
	v_cvt_pk_bf16_f32 v105, v128, v129
	v_addc_co_u32_e32 v131, vcc, 0, v115, vcc
	global_store_dwordx4 v[130:131], v[102:105], off sc0 sc1
	v_mov_b32_e32 v161, 0
	s_nop 0
	v_mul_f32_e32 v102, v123, v123
	v_mul_f32_e32 v103, v125, v125
	v_fmac_f32_e32 v102, v122, v122
	v_fmac_f32_e32 v103, v124, v124
	v_add_f32_e32 v102, v102, v103
	v_mul_f32_e32 v103, v127, v127
	v_mul_f32_e32 v104, v129, v129
	v_fmac_f32_e32 v103, v126, v126
	v_fmac_f32_e32 v104, v128, v128
	v_add_f32_e32 v103, v103, v104
	v_add_f32_e32 v102, v102, v103
	v_mov_b32_e32 v103, 0
	s_nop 0
	v_add_f32_dpp v102, v102, v102 quad_perm:[1,0,3,2] row_mask:0xf bank_mask:0xf bound_ctrl:1
	s_nop 1
	v_add_f32_dpp v102, v102, v102 quad_perm:[2,3,0,1] row_mask:0xf bank_mask:0xf bound_ctrl:1
	s_nop 1
	v_mov_b32_dpp v103, v102 row_half_mirror row_mask:0xf bank_mask:0xf
	s_and_saveexec_b64 s[8:9], s[4:5]
	s_cbranch_execz .LBB0_416
	v_add_f32_e32 v104, v102, v103
	v_lshl_add_u64 v[102:103], s[0:1], 0, v[112:113]
	v_lshl_add_u64 v[102:103], s[6:7], 2, v[102:103]
	v_lshl_add_u64 v[102:103], v[102:103], 0, v[160:161]
	v_add_co_u32_e32 v102, vcc, 0x1000, v102
	s_nop 1
	v_addc_co_u32_e32 v103, vcc, 0, v103, vcc
	global_store_dword v[102:103], v104, off offset:2048
.LBB0_416:
	s_or_b64 exec, exec, s[8:9]
	v_add_u32_e32 v102, 0x1c700, v1
	v_add_u32_e32 v103, 0x1c710, v1
	ds_read_b128 v[122:125], v102
	ds_read_b128 v[126:129], v103
	v_lshlrev_b32_e32 v104, 16, v98
	v_and_b32_e32 v105, 0xffff0000, v98
	v_lshlrev_b32_e32 v98, 16, v99
	v_and_b32_e32 v99, 0xffff0000, v99
	s_waitcnt lgkmcnt(1)
	v_pk_fma_f32 v[124:125], v[124:125], 0.5, v[98:99] op_sel_hi:[1,0,1]
	v_lshlrev_b32_e32 v98, 16, v100
	v_and_b32_e32 v99, 0xffff0000, v100
	v_lshlrev_b32_e32 v100, 16, v101
	v_and_b32_e32 v101, 0xffff0000, v101
	s_mov_b32 s8, 0x38000
	v_pk_fma_f32 v[104:105], v[122:123], 0.5, v[104:105] op_sel_hi:[1,0,1]
	s_waitcnt lgkmcnt(0)
	v_pk_fma_f32 v[122:123], v[128:129], 0.5, v[100:101] op_sel_hi:[1,0,1]
	v_pk_fma_f32 v[126:127], v[126:127], 0.5, v[98:99] op_sel_hi:[1,0,1]
	v_add_co_u32_e32 v114, vcc, s8, v114
	v_cvt_pk_bf16_f32 v98, v104, v105
	v_cvt_pk_bf16_f32 v99, v124, v125
	v_cvt_pk_bf16_f32 v100, v126, v127
	v_cvt_pk_bf16_f32 v101, v122, v123
	v_addc_co_u32_e32 v115, vcc, 0, v115, vcc
	global_store_dwordx4 v[114:115], v[98:101], off sc0 sc1
	s_nop 1
	v_mul_f32_e32 v98, v105, v105
	v_mul_f32_e32 v99, v125, v125
	v_fmac_f32_e32 v98, v104, v104
	v_fmac_f32_e32 v99, v124, v124
	v_add_f32_e32 v98, v98, v99
	v_mul_f32_e32 v99, v127, v127
	v_mul_f32_e32 v100, v123, v123
	v_fmac_f32_e32 v99, v126, v126
	v_fmac_f32_e32 v100, v122, v122
	v_add_f32_e32 v99, v99, v100
	v_add_f32_e32 v98, v98, v99
	s_nop 1
	v_add_f32_dpp v98, v98, v98 quad_perm:[1,0,3,2] row_mask:0xf bank_mask:0xf bound_ctrl:1
	s_nop 1
	v_add_f32_dpp v98, v98, v98 quad_perm:[2,3,0,1] row_mask:0xf bank_mask:0xf bound_ctrl:1
	s_nop 1
	v_mov_b32_dpp v161, v98 row_half_mirror row_mask:0xf bank_mask:0xf
	s_and_saveexec_b64 s[8:9], s[4:5]
	s_cbranch_execz .LBB0_418
	v_add_f32_e32 v100, v98, v161
	v_lshl_add_u64 v[98:99], s[0:1], 0, v[112:113]
	v_lshl_add_u64 v[98:99], s[6:7], 2, v[98:99]
	v_mov_b32_e32 v161, 0
	v_lshl_add_u64 v[98:99], v[98:99], 0, v[160:161]
	v_add_co_u32_e32 v98, vcc, 0x1000, v98
	s_nop 1
	v_addc_co_u32_e32 v99, vcc, 0, v99, vcc
	global_store_dword v[98:99], v100, off offset:3072
.LBB0_418:
	s_or_b64 exec, exec, s[8:9]
	s_barrier
	ds_write_b128 v162, v[6:9]
	ds_write_b128 v162, v[10:13] offset:64
	ds_write_b128 v162, v[14:17] offset:16640
	ds_write_b128 v162, v[18:21] offset:16704
	ds_write_b128 v162, v[22:25] offset:33280
	ds_write_b128 v162, v[26:29] offset:33344
	ds_write_b128 v162, v[30:33] offset:49920
	ds_write_b128 v162, v[34:37] offset:49984
	ds_write_b128 v162, v[38:41] offset:512
	ds_write_b128 v162, v[42:45] offset:576
	ds_write_b128 v162, v[46:49] offset:17152
	ds_write_b128 v162, v[50:53] offset:17216
	ds_write_b128 v162, v[54:57] offset:33792
	ds_write_b128 v162, v[62:65] offset:33856
	ds_write_b128 v162, v[66:69] offset:50432
	ds_write_b128 v162, v[70:73] offset:50496
	s_waitcnt lgkmcnt(0)
	s_barrier
	ds_read_b128 v[6:9], v1
	ds_read_b128 v[10:13], v1 offset:16
	s_waitcnt vmcnt(15)
	v_lshlrev_b32_e32 v14, 16, v94
	v_and_b32_e32 v15, 0xffff0000, v94
	v_lshlrev_b32_e32 v16, 16, v95
	v_and_b32_e32 v17, 0xffff0000, v95
	s_waitcnt lgkmcnt(1)
	v_pk_fma_f32 v[16:17], v[8:9], 0.5, v[16:17] op_sel_hi:[1,0,1]
	v_pk_fma_f32 v[14:15], v[6:7], 0.5, v[14:15] op_sel_hi:[1,0,1]
	v_lshlrev_b32_e32 v6, 16, v96
	v_and_b32_e32 v7, 0xffff0000, v96
	v_lshlrev_b32_e32 v8, 16, v97
	v_and_b32_e32 v9, 0xffff0000, v97
	s_waitcnt lgkmcnt(0)
	v_pk_fma_f32 v[12:13], v[12:13], 0.5, v[8:9] op_sel_hi:[1,0,1]
	v_pk_fma_f32 v[18:19], v[10:11], 0.5, v[6:7] op_sel_hi:[1,0,1]
	v_cvt_pk_bf16_f32 v8, v14, v15
	v_cvt_pk_bf16_f32 v9, v16, v17
	v_cvt_pk_bf16_f32 v10, v18, v19
	v_cvt_pk_bf16_f32 v11, v12, v13
	v_lshl_add_u64 v[6:7], v[110:111], 1, v[108:109]
	global_store_dwordx4 v[6:7], v[8:11], off sc0 sc1
	v_mov_b32_e32 v161, 0
	s_nop 0
	v_mul_f32_e32 v8, v15, v15
	v_mul_f32_e32 v9, v17, v17
	v_fmac_f32_e32 v8, v14, v14
	v_fmac_f32_e32 v9, v16, v16
	v_add_f32_e32 v8, v8, v9
	v_mul_f32_e32 v9, v19, v19
	v_mul_f32_e32 v10, v13, v13
	v_fmac_f32_e32 v9, v18, v18
	v_fmac_f32_e32 v10, v12, v12
	v_add_f32_e32 v9, v9, v10
	v_add_f32_e32 v8, v8, v9
	v_mov_b32_e32 v9, 0
	s_nop 0
	v_add_f32_dpp v8, v8, v8 quad_perm:[1,0,3,2] row_mask:0xf bank_mask:0xf bound_ctrl:1
	s_nop 1
	v_add_f32_dpp v8, v8, v8 quad_perm:[2,3,0,1] row_mask:0xf bank_mask:0xf bound_ctrl:1
	s_nop 1
	v_mov_b32_dpp v9, v8 row_half_mirror row_mask:0xf bank_mask:0xf
	s_and_saveexec_b64 s[8:9], s[4:5]
	s_cbranch_execz .LBB0_420
	v_add_f32_e32 v10, v8, v9
	v_lshlrev_b64 v[8:9], 6, v[106:107]
	v_lshl_add_u64 v[8:9], s[0:1], 0, v[8:9]
	v_lshl_add_u64 v[8:9], s[6:7], 2, v[8:9]
	v_lshl_add_u64 v[8:9], v[8:9], 0, v[160:161]
	global_store_dword v[8:9], v10, off
.LBB0_420:
	s_or_b64 exec, exec, s[8:9]
	ds_read_b128 v[8:11], v1 offset:16640
	ds_read_b128 v[12:15], v1 offset:16656
	s_waitcnt vmcnt(15)
	v_lshlrev_b32_e32 v16, 16, v90
	v_and_b32_e32 v17, 0xffff0000, v90
	v_lshlrev_b32_e32 v18, 16, v91
	v_and_b32_e32 v19, 0xffff0000, v91
	s_waitcnt lgkmcnt(1)
	v_pk_fma_f32 v[18:19], v[10:11], 0.5, v[18:19] op_sel_hi:[1,0,1]
	v_pk_fma_f32 v[16:17], v[8:9], 0.5, v[16:17] op_sel_hi:[1,0,1]
	v_lshlrev_b32_e32 v8, 16, v92
	v_and_b32_e32 v9, 0xffff0000, v92
	v_lshlrev_b32_e32 v10, 16, v93
	v_and_b32_e32 v11, 0xffff0000, v93
	s_mov_b32 s8, 0x8000
	s_waitcnt lgkmcnt(0)
	v_pk_fma_f32 v[14:15], v[14:15], 0.5, v[10:11] op_sel_hi:[1,0,1]
	v_pk_fma_f32 v[12:13], v[12:13], 0.5, v[8:9] op_sel_hi:[1,0,1]
	v_add_co_u32_e32 v20, vcc, s8, v6
	v_cvt_pk_bf16_f32 v8, v16, v17
	v_cvt_pk_bf16_f32 v9, v18, v19
	v_cvt_pk_bf16_f32 v10, v12, v13
	v_cvt_pk_bf16_f32 v11, v14, v15
	v_addc_co_u32_e32 v21, vcc, 0, v7, vcc
	global_store_dwordx4 v[20:21], v[8:11], off sc0 sc1
	s_nop 1
	v_mul_f32_e32 v8, v17, v17
	v_mul_f32_e32 v9, v19, v19
	v_fmac_f32_e32 v8, v16, v16
	v_fmac_f32_e32 v9, v18, v18
	v_add_f32_e32 v8, v8, v9
	v_mul_f32_e32 v9, v13, v13
	v_mul_f32_e32 v10, v15, v15
	v_fmac_f32_e32 v9, v12, v12
	v_fmac_f32_e32 v10, v14, v14
	v_add_f32_e32 v9, v9, v10
	v_add_f32_e32 v8, v8, v9
	s_nop 1
	v_add_f32_dpp v8, v8, v8 quad_perm:[1,0,3,2] row_mask:0xf bank_mask:0xf bound_ctrl:1
	s_nop 1
	v_add_f32_dpp v8, v8, v8 quad_perm:[2,3,0,1] row_mask:0xf bank_mask:0xf bound_ctrl:1
	s_nop 1
	v_mov_b32_dpp v161, v8 row_half_mirror row_mask:0xf bank_mask:0xf
	s_and_saveexec_b64 s[8:9], s[4:5]
	s_cbranch_execz .LBB0_422
	v_add_f32_e32 v10, v8, v161
	v_add_u32_e32 v8, 0x90, v158
	v_ashrrev_i32_e32 v9, 31, v8
	v_lshlrev_b64 v[8:9], 6, v[8:9]
	v_lshl_add_u64 v[8:9], s[0:1], 0, v[8:9]
	v_lshl_add_u64 v[8:9], s[6:7], 2, v[8:9]
	v_mov_b32_e32 v161, 0
	v_lshl_add_u64 v[8:9], v[8:9], 0, v[160:161]
	global_store_dword v[8:9], v10, off
.LBB0_422:
	s_or_b64 exec, exec, s[8:9]
	ds_read_b128 v[8:11], v1 offset:33280
	ds_read_b128 v[12:15], v1 offset:33296
	s_waitcnt vmcnt(15)
	v_lshlrev_b32_e32 v16, 16, v86
	v_and_b32_e32 v17, 0xffff0000, v86
	v_lshlrev_b32_e32 v18, 16, v87
	v_and_b32_e32 v19, 0xffff0000, v87
	s_waitcnt lgkmcnt(1)
	v_pk_fma_f32 v[18:19], v[10:11], 0.5, v[18:19] op_sel_hi:[1,0,1]
	v_pk_fma_f32 v[16:17], v[8:9], 0.5, v[16:17] op_sel_hi:[1,0,1]
	v_lshlrev_b32_e32 v8, 16, v88
	v_and_b32_e32 v9, 0xffff0000, v88
	v_lshlrev_b32_e32 v10, 16, v89
	v_and_b32_e32 v11, 0xffff0000, v89
	s_mov_b32 s8, 0x10000
	s_waitcnt lgkmcnt(0)
	v_pk_fma_f32 v[14:15], v[14:15], 0.5, v[10:11] op_sel_hi:[1,0,1]
	v_pk_fma_f32 v[12:13], v[12:13], 0.5, v[8:9] op_sel_hi:[1,0,1]
	v_add_co_u32_e32 v20, vcc, s8, v6
	v_cvt_pk_bf16_f32 v8, v16, v17
	v_cvt_pk_bf16_f32 v9, v18, v19
	v_cvt_pk_bf16_f32 v10, v12, v13
	v_cvt_pk_bf16_f32 v11, v14, v15
	v_addc_co_u32_e32 v21, vcc, 0, v7, vcc
	global_store_dwordx4 v[20:21], v[8:11], off sc0 sc1
	v_mov_b32_e32 v161, 0
	s_nop 0
	v_mul_f32_e32 v8, v17, v17
	v_mul_f32_e32 v9, v19, v19
	v_fmac_f32_e32 v8, v16, v16
	v_fmac_f32_e32 v9, v18, v18
	v_add_f32_e32 v8, v8, v9
	v_mul_f32_e32 v9, v13, v13
	v_mul_f32_e32 v10, v15, v15
	v_fmac_f32_e32 v9, v12, v12
	v_fmac_f32_e32 v10, v14, v14
	v_add_f32_e32 v9, v9, v10
	v_add_f32_e32 v8, v8, v9
	v_mov_b32_e32 v9, 0
	s_nop 0
	v_add_f32_dpp v8, v8, v8 quad_perm:[1,0,3,2] row_mask:0xf bank_mask:0xf bound_ctrl:1
	s_nop 1
	v_add_f32_dpp v8, v8, v8 quad_perm:[2,3,0,1] row_mask:0xf bank_mask:0xf bound_ctrl:1
	s_nop 1
	v_mov_b32_dpp v9, v8 row_half_mirror row_mask:0xf bank_mask:0xf
	s_and_saveexec_b64 s[8:9], s[4:5]
	s_cbranch_execz .LBB0_424
	v_add_f32_e32 v10, v8, v9
	v_add_u32_e32 v8, 0xa0, v158
	v_ashrrev_i32_e32 v9, 31, v8
	v_lshlrev_b64 v[8:9], 6, v[8:9]
	v_lshl_add_u64 v[8:9], s[0:1], 0, v[8:9]
	v_lshl_add_u64 v[8:9], s[6:7], 2, v[8:9]
	v_lshl_add_u64 v[8:9], v[8:9], 0, v[160:161]
	global_store_dword v[8:9], v10, off
.LBB0_424:
	s_or_b64 exec, exec, s[8:9]
	ds_read_b128 v[8:11], v1 offset:49920
	ds_read_b128 v[12:15], v1 offset:49936
	s_waitcnt vmcnt(15)
	v_lshlrev_b32_e32 v16, 16, v82
	v_and_b32_e32 v17, 0xffff0000, v82
	v_lshlrev_b32_e32 v18, 16, v83
	v_and_b32_e32 v19, 0xffff0000, v83
	s_waitcnt lgkmcnt(1)
	v_pk_fma_f32 v[18:19], v[10:11], 0.5, v[18:19] op_sel_hi:[1,0,1]
	v_pk_fma_f32 v[16:17], v[8:9], 0.5, v[16:17] op_sel_hi:[1,0,1]
	v_lshlrev_b32_e32 v8, 16, v84
	v_and_b32_e32 v9, 0xffff0000, v84
	v_lshlrev_b32_e32 v10, 16, v85
	v_and_b32_e32 v11, 0xffff0000, v85
	s_mov_b32 s8, 0x18000
	s_waitcnt lgkmcnt(0)
	v_pk_fma_f32 v[14:15], v[14:15], 0.5, v[10:11] op_sel_hi:[1,0,1]
	v_pk_fma_f32 v[12:13], v[12:13], 0.5, v[8:9] op_sel_hi:[1,0,1]
	v_add_co_u32_e32 v20, vcc, s8, v6
	v_cvt_pk_bf16_f32 v8, v16, v17
	v_cvt_pk_bf16_f32 v9, v18, v19
	v_cvt_pk_bf16_f32 v10, v12, v13
	v_cvt_pk_bf16_f32 v11, v14, v15
	v_addc_co_u32_e32 v21, vcc, 0, v7, vcc
	global_store_dwordx4 v[20:21], v[8:11], off sc0 sc1
	v_mul_f32_e32 v1, v17, v17
	v_fmac_f32_e32 v1, v16, v16
	v_mul_f32_e32 v8, v19, v19
	v_fmac_f32_e32 v8, v18, v18
	v_add_f32_e32 v1, v1, v8
	v_mul_f32_e32 v8, v13, v13
	v_mul_f32_e32 v9, v15, v15
	v_fmac_f32_e32 v8, v12, v12
	v_fmac_f32_e32 v9, v14, v14
	v_add_f32_e32 v8, v8, v9
	v_add_f32_e32 v1, v1, v8
	s_nop 1
	v_add_f32_dpp v1, v1, v1 quad_perm:[1,0,3,2] row_mask:0xf bank_mask:0xf bound_ctrl:1
	s_nop 1
	v_add_f32_dpp v1, v1, v1 quad_perm:[2,3,0,1] row_mask:0xf bank_mask:0xf bound_ctrl:1
	s_nop 1
	v_mov_b32_dpp v161, v1 row_half_mirror row_mask:0xf bank_mask:0xf
	s_and_saveexec_b64 s[8:9], s[4:5]
	s_cbranch_execz .LBB0_426
	v_add_u32_e32 v8, 0xb0, v158
	v_ashrrev_i32_e32 v9, 31, v8
	v_lshlrev_b64 v[8:9], 6, v[8:9]
	v_lshl_add_u64 v[8:9], s[0:1], 0, v[8:9]
	v_add_f32_e32 v1, v1, v161
	v_lshl_add_u64 v[8:9], s[6:7], 2, v[8:9]
	v_mov_b32_e32 v161, 0
	v_lshl_add_u64 v[8:9], v[8:9], 0, v[160:161]
	global_store_dword v[8:9], v1, off
.LBB0_426:
	s_or_b64 exec, exec, s[8:9]
	ds_read_b128 v[8:11], v116
	ds_read_b128 v[12:15], v117
	s_waitcnt vmcnt(15)
	v_lshlrev_b32_e32 v16, 16, v78
	v_and_b32_e32 v17, 0xffff0000, v78
	v_lshlrev_b32_e32 v18, 16, v79
	v_and_b32_e32 v19, 0xffff0000, v79
	s_waitcnt lgkmcnt(1)
	v_pk_fma_f32 v[18:19], v[10:11], 0.5, v[18:19] op_sel_hi:[1,0,1]
	v_pk_fma_f32 v[16:17], v[8:9], 0.5, v[16:17] op_sel_hi:[1,0,1]
	v_lshlrev_b32_e32 v8, 16, v80
	v_and_b32_e32 v9, 0xffff0000, v80
	v_lshlrev_b32_e32 v10, 16, v81
	v_and_b32_e32 v11, 0xffff0000, v81
	s_mov_b32 s8, 0x20000
	s_waitcnt lgkmcnt(0)
	v_pk_fma_f32 v[14:15], v[14:15], 0.5, v[10:11] op_sel_hi:[1,0,1]
	v_pk_fma_f32 v[12:13], v[12:13], 0.5, v[8:9] op_sel_hi:[1,0,1]
	v_add_co_u32_e32 v20, vcc, s8, v6
	v_cvt_pk_bf16_f32 v8, v16, v17
	v_cvt_pk_bf16_f32 v9, v18, v19
	v_cvt_pk_bf16_f32 v10, v12, v13
	v_cvt_pk_bf16_f32 v11, v14, v15
	v_addc_co_u32_e32 v21, vcc, 0, v7, vcc
	global_store_dwordx4 v[20:21], v[8:11], off sc0 sc1
	v_mul_f32_e32 v1, v17, v17
	v_fmac_f32_e32 v1, v16, v16
	v_mul_f32_e32 v8, v19, v19
	v_fmac_f32_e32 v8, v18, v18
	v_add_f32_e32 v1, v1, v8
	v_mul_f32_e32 v8, v13, v13
	v_mul_f32_e32 v9, v15, v15
	v_fmac_f32_e32 v8, v12, v12
	v_fmac_f32_e32 v9, v14, v14
	v_add_f32_e32 v8, v8, v9
	v_add_f32_e32 v1, v1, v8
	v_mov_b32_e32 v8, 0
	v_mov_b32_e32 v161, 0
	v_add_f32_dpp v1, v1, v1 quad_perm:[1,0,3,2] row_mask:0xf bank_mask:0xf bound_ctrl:1
	s_nop 1
	v_add_f32_dpp v1, v1, v1 quad_perm:[2,3,0,1] row_mask:0xf bank_mask:0xf bound_ctrl:1
	s_nop 1
	v_mov_b32_dpp v8, v1 row_half_mirror row_mask:0xf bank_mask:0xf
	s_and_saveexec_b64 s[8:9], s[4:5]
	s_cbranch_execz .LBB0_428
	v_add_f32_e32 v1, v1, v8
	v_add_u32_e32 v8, 0xc0, v158
	v_ashrrev_i32_e32 v9, 31, v8
	v_lshlrev_b64 v[8:9], 6, v[8:9]
	v_lshl_add_u64 v[8:9], s[0:1], 0, v[8:9]
	v_lshl_add_u64 v[8:9], s[6:7], 2, v[8:9]
	v_lshl_add_u64 v[8:9], v[8:9], 0, v[160:161]
	global_store_dword v[8:9], v1, off
.LBB0_428:
	s_or_b64 exec, exec, s[8:9]
	ds_read_b128 v[8:11], v118
	ds_read_b128 v[12:15], v119
	s_waitcnt vmcnt(15)
	v_lshlrev_b32_e32 v16, 16, v74
	v_and_b32_e32 v17, 0xffff0000, v74
	v_lshlrev_b32_e32 v18, 16, v75
	v_and_b32_e32 v19, 0xffff0000, v75
	s_waitcnt lgkmcnt(1)
	v_pk_fma_f32 v[18:19], v[10:11], 0.5, v[18:19] op_sel_hi:[1,0,1]
	v_pk_fma_f32 v[16:17], v[8:9], 0.5, v[16:17] op_sel_hi:[1,0,1]
	v_lshlrev_b32_e32 v8, 16, v76
	v_and_b32_e32 v9, 0xffff0000, v76
	v_lshlrev_b32_e32 v10, 16, v77
	v_and_b32_e32 v11, 0xffff0000, v77
	s_mov_b32 s8, 0x28000
	s_waitcnt lgkmcnt(0)
	v_pk_fma_f32 v[14:15], v[14:15], 0.5, v[10:11] op_sel_hi:[1,0,1]
	v_pk_fma_f32 v[12:13], v[12:13], 0.5, v[8:9] op_sel_hi:[1,0,1]
	v_add_co_u32_e32 v20, vcc, s8, v6
	v_cvt_pk_bf16_f32 v8, v16, v17
	v_cvt_pk_bf16_f32 v9, v18, v19
	v_cvt_pk_bf16_f32 v10, v12, v13
	v_cvt_pk_bf16_f32 v11, v14, v15
	v_addc_co_u32_e32 v21, vcc, 0, v7, vcc
	global_store_dwordx4 v[20:21], v[8:11], off sc0 sc1
	v_mul_f32_e32 v1, v17, v17
	v_fmac_f32_e32 v1, v16, v16
	v_mul_f32_e32 v8, v19, v19
	v_fmac_f32_e32 v8, v18, v18
	v_add_f32_e32 v1, v1, v8
	v_mul_f32_e32 v8, v13, v13
	v_mul_f32_e32 v9, v15, v15
	v_fmac_f32_e32 v8, v12, v12
	v_fmac_f32_e32 v9, v14, v14
	v_add_f32_e32 v8, v8, v9
	v_add_f32_e32 v1, v1, v8
	s_nop 1
	v_add_f32_dpp v1, v1, v1 quad_perm:[1,0,3,2] row_mask:0xf bank_mask:0xf bound_ctrl:1
	s_nop 1
	v_add_f32_dpp v1, v1, v1 quad_perm:[2,3,0,1] row_mask:0xf bank_mask:0xf bound_ctrl:1
	s_nop 1
	v_mov_b32_dpp v161, v1 row_half_mirror row_mask:0xf bank_mask:0xf
	s_and_saveexec_b64 s[8:9], s[4:5]
	s_cbranch_execz .LBB0_430
	v_add_u32_e32 v8, 0xd0, v158
	v_ashrrev_i32_e32 v9, 31, v8
	v_lshlrev_b64 v[8:9], 6, v[8:9]
	v_lshl_add_u64 v[8:9], s[0:1], 0, v[8:9]
	v_add_f32_e32 v1, v1, v161
	v_lshl_add_u64 v[8:9], s[6:7], 2, v[8:9]
	v_mov_b32_e32 v161, 0
	v_lshl_add_u64 v[8:9], v[8:9], 0, v[160:161]
	global_store_dword v[8:9], v1, off
.LBB0_430:
	s_or_b64 exec, exec, s[8:9]
	ds_read_b128 v[8:11], v120
	ds_read_b128 v[12:15], v121
	s_waitcnt vmcnt(15)
	v_lshlrev_b32_e32 v16, 16, v58
	v_and_b32_e32 v17, 0xffff0000, v58
	v_lshlrev_b32_e32 v18, 16, v59
	v_and_b32_e32 v19, 0xffff0000, v59
	s_waitcnt lgkmcnt(1)
	v_pk_fma_f32 v[18:19], v[10:11], 0.5, v[18:19] op_sel_hi:[1,0,1]
	v_pk_fma_f32 v[16:17], v[8:9], 0.5, v[16:17] op_sel_hi:[1,0,1]
	v_lshlrev_b32_e32 v8, 16, v60
	v_and_b32_e32 v9, 0xffff0000, v60
	v_lshlrev_b32_e32 v10, 16, v61
	v_and_b32_e32 v11, 0xffff0000, v61
	s_mov_b32 s8, 0x30000
	s_waitcnt lgkmcnt(0)
	v_pk_fma_f32 v[14:15], v[14:15], 0.5, v[10:11] op_sel_hi:[1,0,1]
	v_pk_fma_f32 v[12:13], v[12:13], 0.5, v[8:9] op_sel_hi:[1,0,1]
	v_add_co_u32_e32 v20, vcc, s8, v6
	v_cvt_pk_bf16_f32 v8, v16, v17
	v_cvt_pk_bf16_f32 v9, v18, v19
	v_cvt_pk_bf16_f32 v10, v12, v13
	v_cvt_pk_bf16_f32 v11, v14, v15
	v_addc_co_u32_e32 v21, vcc, 0, v7, vcc
	global_store_dwordx4 v[20:21], v[8:11], off sc0 sc1
	v_mul_f32_e32 v1, v17, v17
	v_fmac_f32_e32 v1, v16, v16
	v_mul_f32_e32 v8, v19, v19
	v_fmac_f32_e32 v8, v18, v18
	v_add_f32_e32 v1, v1, v8
	v_mul_f32_e32 v8, v13, v13
	v_mul_f32_e32 v9, v15, v15
	v_fmac_f32_e32 v8, v12, v12
	v_fmac_f32_e32 v9, v14, v14
	v_add_f32_e32 v8, v8, v9
	v_add_f32_e32 v1, v1, v8
	v_mov_b32_e32 v8, 0
	v_mov_b32_e32 v161, 0
	v_add_f32_dpp v1, v1, v1 quad_perm:[1,0,3,2] row_mask:0xf bank_mask:0xf bound_ctrl:1
	s_nop 1
	v_add_f32_dpp v1, v1, v1 quad_perm:[2,3,0,1] row_mask:0xf bank_mask:0xf bound_ctrl:1
	s_nop 1
	v_mov_b32_dpp v8, v1 row_half_mirror row_mask:0xf bank_mask:0xf
	s_and_saveexec_b64 s[8:9], s[4:5]
	s_cbranch_execz .LBB0_432
	v_add_f32_e32 v1, v1, v8
	v_add_u32_e32 v8, 0xe0, v158
	v_ashrrev_i32_e32 v9, 31, v8
	v_lshlrev_b64 v[8:9], 6, v[8:9]
	v_lshl_add_u64 v[8:9], s[0:1], 0, v[8:9]
	v_lshl_add_u64 v[8:9], s[6:7], 2, v[8:9]
	v_lshl_add_u64 v[8:9], v[8:9], 0, v[160:161]
	global_store_dword v[8:9], v1, off
.LBB0_432:
	s_or_b64 exec, exec, s[8:9]
	ds_read_b128 v[8:11], v102
	ds_read_b128 v[12:15], v103
	s_waitcnt vmcnt(15)
	v_lshlrev_b32_e32 v16, 16, v2
	v_and_b32_e32 v17, 0xffff0000, v2
	v_lshlrev_b32_e32 v2, 16, v3
	v_and_b32_e32 v3, 0xffff0000, v3
	s_waitcnt lgkmcnt(1)
	v_pk_fma_f32 v[10:11], v[10:11], 0.5, v[2:3] op_sel_hi:[1,0,1]
	v_lshlrev_b32_e32 v2, 16, v4
	v_and_b32_e32 v3, 0xffff0000, v4
	v_lshlrev_b32_e32 v4, 16, v5
	v_and_b32_e32 v5, 0xffff0000, v5
	s_mov_b32 s8, 0x38000
	v_pk_fma_f32 v[8:9], v[8:9], 0.5, v[16:17] op_sel_hi:[1,0,1]
	s_waitcnt lgkmcnt(0)
	v_pk_fma_f32 v[14:15], v[14:15], 0.5, v[4:5] op_sel_hi:[1,0,1]
	v_pk_fma_f32 v[12:13], v[12:13], 0.5, v[2:3] op_sel_hi:[1,0,1]
	v_add_co_u32_e32 v6, vcc, s8, v6
	v_cvt_pk_bf16_f32 v2, v8, v9
	v_cvt_pk_bf16_f32 v3, v10, v11
	v_cvt_pk_bf16_f32 v4, v12, v13
	v_cvt_pk_bf16_f32 v5, v14, v15
	v_addc_co_u32_e32 v7, vcc, 0, v7, vcc
	global_store_dwordx4 v[6:7], v[2:5], off sc0 sc1
	v_mul_f32_e32 v1, v9, v9
	v_fmac_f32_e32 v1, v8, v8
	v_mul_f32_e32 v2, v11, v11
	v_fmac_f32_e32 v2, v10, v10
	v_add_f32_e32 v1, v1, v2
	v_mul_f32_e32 v2, v13, v13
	v_mul_f32_e32 v3, v15, v15
	v_fmac_f32_e32 v2, v12, v12
	v_fmac_f32_e32 v3, v14, v14
	v_add_f32_e32 v2, v2, v3
	v_add_f32_e32 v1, v1, v2
	s_nop 1
	v_add_f32_dpp v1, v1, v1 quad_perm:[1,0,3,2] row_mask:0xf bank_mask:0xf bound_ctrl:1
	s_nop 1
	v_add_f32_dpp v1, v1, v1 quad_perm:[2,3,0,1] row_mask:0xf bank_mask:0xf bound_ctrl:1
	s_nop 1
	v_mov_b32_dpp v161, v1 row_half_mirror row_mask:0xf bank_mask:0xf
	s_and_saveexec_b64 s[8:9], s[4:5]
	s_cbranch_execz .LBB0_434
	v_add_u32_e32 v2, 0xf0, v158
	v_ashrrev_i32_e32 v3, 31, v2
	v_lshlrev_b64 v[2:3], 6, v[2:3]
	v_lshl_add_u64 v[2:3], s[0:1], 0, v[2:3]
	v_add_f32_e32 v1, v1, v161
	v_lshl_add_u64 v[2:3], s[6:7], 2, v[2:3]
	v_mov_b32_e32 v161, 0
	v_lshl_add_u64 v[2:3], v[2:3], 0, v[160:161]
	global_store_dword v[2:3], v1, off

.LBB0_1007:
	v_bfe_u32 v58, v1, 5, 1
	v_or_b32_e32 v2, s22, v145
	v_lshlrev_b32_e32 v59, 4, v58
	v_mul_u32_u24_e32 v2, 0x110, v2
	v_add3_u32 v54, 0, v2, v59
	s_waitcnt lgkmcnt(0)
	s_barrier
	ds_read_b128 v[2:5], v54
	v_or_b32_e32 v6, s21, v145
	v_mul_lo_u32 v60, v6, s43
	v_add3_u32 v50, s34, v60, v59
	ds_read_b128 v[18:21], v50
	ds_read_b128 v[22:25], v50 offset:32
	ds_read_b128 v[26:29], v54 offset:32
	s_waitcnt lgkmcnt(2)
	v_mfma_f32_32x32x16_bf16 v[2:17], v[2:5], v[18:21], 0
	v_lshlrev_b32_e32 v58, 3, v58
	v_add_u32_e32 v60, s44, v60
	s_and_b64 s[4:5], exec, s[4:5]
	s_cselect_b32 s0, 1, 0x3fffffff
	s_lshl_b32 s4, s52, 9
	s_add_i32 s0, s53, s0
	s_add_i32 s4, s4, s51
	s_waitcnt lgkmcnt(0)
	v_mfma_f32_32x32x16_bf16 v[2:17], v[26:29], v[22:25], v[2:17]
	ds_read_b128 v[26:29], v54 offset:64
	ds_read_b128 v[30:33], v50 offset:64
	ds_read_b128 v[34:37], v50 offset:96
	ds_read_b128 v[38:41], v54 offset:96
	s_lshl_b32 s0, s0, 2
	s_add_i32 s0, s4, s0
	s_add_i32 s4, s0, -4
	s_ashr_i32 s5, s4, 31
	s_lshl_b64 s[4:5], s[4:5], 15
	s_add_u32 s4, s84, s4
	s_waitcnt lgkmcnt(2)
	v_mfma_f32_32x32x16_bf16 v[2:17], v[26:29], v[30:33], v[2:17]
	s_addc_u32 s5, s85, s5
	s_add_i32 s50, s50, 1
	s_cmp_eq_u32 s50, 4
	s_waitcnt lgkmcnt(0)
	v_mfma_f32_32x32x16_bf16 v[2:17], v[38:41], v[34:37], v[2:17]
	ds_read_b128 v[26:29], v54 offset:128
	ds_read_b128 v[38:41], v50 offset:128
	ds_read_b128 v[42:45], v50 offset:160
	ds_read_b128 v[46:49], v54 offset:160
	s_waitcnt lgkmcnt(2)
	v_mfma_f32_32x32x16_bf16 v[2:17], v[26:29], v[38:41], v[2:17]
	s_waitcnt lgkmcnt(0)
	v_mfma_f32_32x32x16_bf16 v[2:17], v[46:49], v[42:45], v[2:17]
	ds_read_b128 v[26:29], v54 offset:192
	ds_read_b128 v[46:49], v50 offset:192
	ds_read_b128 v[50:53], v50 offset:224
	ds_read_b128 v[54:57], v54 offset:224
	s_waitcnt lgkmcnt(2)
	v_mfma_f32_32x32x16_bf16 v[2:17], v[26:29], v[46:49], v[2:17]
	v_or_b32_e32 v26, s24, v145
	v_mul_u32_u24_e32 v26, 0x110, v26
	v_add3_u32 v59, 0, v26, v59
	v_add3_u32 v26, v60, s23, v58
	s_waitcnt lgkmcnt(0)
	v_mfma_f32_32x32x16_bf16 v[2:17], v[54:57], v[50:53], v[2:17]
	v_lshlrev_b32_e32 v55, 4, v1
	v_ashrrev_i32_e32 v54, 4, v1
	v_add_u32_e32 v56, 0x200, v1
	v_add_u32_e32 v57, 0x400, v1
	v_add_u32_e32 v1, 0x600, v1
	v_and_b32_e32 v70, 0xf0, v55
	v_ashrrev_i32_e32 v55, 31, v54
	s_nop 4
	v_cvt_pk_bf16_f32 v2, v2, v3
	v_cvt_pk_bf16_f32 v3, v4, v5
	v_cvt_pk_bf16_f32 v4, v6, v7
	v_cvt_pk_bf16_f32 v5, v8, v9
	v_cvt_pk_bf16_f32 v6, v10, v11
	v_cvt_pk_bf16_f32 v7, v12, v13
	v_cvt_pk_bf16_f32 v8, v14, v15
	v_cvt_pk_bf16_f32 v9, v16, v17
	ds_write2_b64 v26, v[2:3], v[4:5] offset1:2
	ds_write2_b64 v26, v[6:7], v[8:9] offset0:4 offset1:6
	ds_read_b128 v[2:5], v59
	ds_read_b128 v[26:29], v59 offset:32
	s_waitcnt lgkmcnt(1)
	v_mfma_f32_32x32x16_bf16 v[2:17], v[2:5], v[18:21], 0
	ds_read_b128 v[18:21], v59 offset:64
	s_waitcnt lgkmcnt(1)
	v_mfma_f32_32x32x16_bf16 v[2:17], v[26:29], v[22:25], v[2:17]
	ds_read_b128 v[22:25], v59 offset:96
	v_mul_lo_u32 v27, v54, s43
	v_ashrrev_i32_e32 v26, 4, v56
	v_ashrrev_i32_e32 v28, 4, v57
	v_ashrrev_i32_e32 v29, 31, v28
	s_waitcnt lgkmcnt(1)
	v_mfma_f32_32x32x16_bf16 v[2:17], v[18:21], v[30:33], v[2:17]
	ds_read_b128 v[18:21], v59 offset:128
	v_ashrrev_i32_e32 v30, 4, v1
	v_add3_u32 v1, s44, v27, v70
	v_lshlrev_b64 v[32:33], 8, v[54:55]
	v_mul_lo_u32 v54, v26, s43
	v_ashrrev_i32_e32 v27, 31, v26
	v_ashrrev_i32_e32 v31, 31, v30
	s_waitcnt lgkmcnt(1)
	v_mfma_f32_32x32x16_bf16 v[2:17], v[22:25], v[34:37], v[2:17]
	ds_read_b128 v[22:25], v59 offset:160
	v_mul_lo_u32 v34, v28, s43
	v_mul_lo_u32 v35, v30, s43
	v_add3_u32 v36, v60, s25, v58
	v_add3_u32 v37, s44, v54, v70
	v_add3_u32 v34, s44, v34, v70
	v_add3_u32 v35, s44, v35, v70
	s_waitcnt lgkmcnt(1)
	v_mfma_f32_32x32x16_bf16 v[2:17], v[18:21], v[38:41], v[2:17]
	ds_read_b128 v[18:21], v59 offset:192
	v_lshlrev_b64 v[26:27], 8, v[26:27]
	v_lshlrev_b64 v[28:29], 8, v[28:29]
	v_lshlrev_b64 v[30:31], 8, v[30:31]
	s_waitcnt lgkmcnt(1)
	v_mfma_f32_32x32x16_bf16 v[2:17], v[22:25], v[42:45], v[2:17]
	ds_read_b128 v[22:25], v59 offset:224
	s_waitcnt lgkmcnt(1)
	v_mfma_f32_32x32x16_bf16 v[2:17], v[18:21], v[46:49], v[2:17]
	v_lshl_add_u64 v[18:19], s[4:5], 0, v[70:71]
	v_lshl_add_u64 v[20:21], v[18:19], 0, v[32:33]
	v_lshl_add_u64 v[26:27], v[18:19], 0, v[26:27]
	v_lshl_add_u64 v[28:29], v[18:19], 0, v[28:29]
	v_lshl_add_u64 v[18:19], v[18:19], 0, v[30:31]
	s_waitcnt lgkmcnt(0)
	v_mfma_f32_32x32x16_bf16 v[2:17], v[22:25], v[50:53], v[2:17]
	s_nop 11
	v_cvt_pk_bf16_f32 v2, v2, v3
	v_cvt_pk_bf16_f32 v3, v4, v5
	v_cvt_pk_bf16_f32 v4, v6, v7
	v_cvt_pk_bf16_f32 v5, v8, v9
	v_cvt_pk_bf16_f32 v6, v10, v11
	v_cvt_pk_bf16_f32 v7, v12, v13
	v_cvt_pk_bf16_f32 v8, v14, v15
	v_cvt_pk_bf16_f32 v9, v16, v17
	ds_write2_b64 v36, v[2:3], v[4:5] offset1:2
	ds_write2_b64 v36, v[6:7], v[8:9] offset0:4 offset1:6
	s_waitcnt lgkmcnt(0)
	s_barrier
	ds_read_b128 v[2:5], v1
	ds_read_b128 v[6:9], v37
	ds_read_b128 v[10:13], v34
	ds_read_b128 v[14:17], v35
	s_waitcnt lgkmcnt(3)
	global_store_dwordx4 v[20:21], v[2:5], off sc0 sc1
	s_waitcnt lgkmcnt(2)
	global_store_dwordx4 v[26:27], v[6:9], off sc0 sc1
	s_waitcnt lgkmcnt(1)
	global_store_dwordx4 v[28:29], v[10:13], off sc0 sc1
	s_waitcnt lgkmcnt(0)
	global_store_dwordx4 v[18:19], v[14:17], off sc0 sc1
	s_cbranch_scc1 .LBB0_1005

.LBB0_1033:
	v_pk_mul_f32 v[2:3], v[10:11], v[2:3]
	v_pk_mul_f32 v[10:11], v[12:13], v[14:15]
	v_pk_mul_f32 v[4:5], v[16:17], v[4:5]
	v_pk_mul_f32 v[12:13], v[20:21], v[18:19]
	v_cvt_pk_bf16_f32 v2, v2, v3
	v_cvt_pk_bf16_f32 v3, v10, v11
	v_cvt_pk_bf16_f32 v4, v4, v5
	v_cvt_pk_bf16_f32 v5, v12, v13
	v_cmp_gt_u32_e32 vcc, 32, v1
	ds_write_b128 v32, v[2:5] offset:816
	s_and_saveexec_b64 s[6:7], vcc
	s_cbranch_execz .LBB0_1035
	s_and_b64 s[12:13], exec, s[4:5]
	s_cselect_b32 s0, s39, 0x182c00
	s_add_u32 s0, s86, s0
	s_addc_u32 s15, s87, 0
	s_lshl_b32 s12, s53, 9
	s_ashr_i32 s13, s12, 31
	s_lshl_b64 s[12:13], s[12:13], 2
	s_add_u32 s16, s0, s12
	s_addc_u32 s15, s15, s13
	s_lshl_b32 s0, s51, 7
	v_exp_f32_e32 v2, v6
	v_exp_f32_e32 v3, v7
	v_exp_f32_e32 v4, v8
	v_exp_f32_e32 v5, v9
	s_lshl_b64 s[12:13], s[0:1], 2
	s_add_u32 s12, s16, s12
	s_addc_u32 s13, s15, s13
	v_lshlrev_b32_e32 v70, 2, v1
	v_lshl_add_u64 v[6:7], v[70:71], 2, s[12:13]
	global_store_dwordx4 v[6:7], v[2:5], off sc0 sc1

.LBB0_1117:
	s_or_b64 exec, exec, s[24:25]
	s_waitcnt lgkmcnt(0)
	v_lshl_add_u32 v3, v216, 4, s27
	ds_read_b128 v[8:11], v3 offset:128
	ds_read_b128 v[12:15], v3 offset:160
	s_add_i32 s24, s26, 0
	s_add_i32 s24, s24, 0x10800
	v_lshlrev_b32_e32 v69, 1, v215
	s_waitcnt lgkmcnt(1)
	v_rcp_f32_e32 v4, v8
	v_rcp_f32_e32 v5, v9
	v_rcp_f32_e32 v7, v10
	v_rcp_f32_e32 v16, v11
	s_waitcnt lgkmcnt(0)
	v_rcp_f32_e32 v17, v12
	ds_read_b128 v[8:11], v3 offset:192
	v_rcp_f32_e32 v66, v13
	v_rcp_f32_e32 v67, v14
	v_rcp_f32_e32 v68, v15
	ds_read_b128 v[12:15], v3 offset:224
	s_waitcnt lgkmcnt(1)
	v_rcp_f32_e32 v3, v8
	v_rcp_f32_e32 v8, v9
	v_rcp_f32_e32 v9, v10
	v_rcp_f32_e32 v10, v11
	s_waitcnt lgkmcnt(0)
	v_rcp_f32_e32 v11, v12
	v_rcp_f32_e32 v12, v13
	v_rcp_f32_e32 v13, v14
	v_rcp_f32_e32 v14, v15
	v_lshlrev_b32_e32 v15, 9, v216
	v_mul_f32_e32 v34, v34, v4
	v_add3_u32 v15, s24, v15, v69
	v_bfe_u32 v69, v34, 16, 1
	v_add3_u32 v34, v34, v69, s61
	v_mul_f32_e32 v4, v50, v4
	ds_write_b16_d16_hi v15, v34
	v_bfe_u32 v34, v4, 16, 1
	v_add3_u32 v4, v4, v34, s61
	ds_write_b16_d16_hi v15, v4 offset:64
	v_mul_f32_e32 v4, v35, v5
	v_bfe_u32 v34, v4, 16, 1
	v_add3_u32 v4, v4, v34, s61
	ds_write_b16_d16_hi v15, v4 offset:128
	v_mul_f32_e32 v4, v51, v5
	v_bfe_u32 v5, v4, 16, 1
	v_add3_u32 v4, v4, v5, s61
	ds_write_b16_d16_hi v15, v4 offset:192
	v_mul_f32_e32 v4, v36, v7
	v_bfe_u32 v5, v4, 16, 1
	v_add3_u32 v4, v4, v5, s61
	ds_write_b16_d16_hi v15, v4 offset:256
	v_mul_f32_e32 v4, v52, v7
	v_bfe_u32 v5, v4, 16, 1
	v_add3_u32 v4, v4, v5, s61
	ds_write_b16_d16_hi v15, v4 offset:320
	v_mul_f32_e32 v4, v37, v16
	v_bfe_u32 v5, v4, 16, 1
	v_add3_u32 v4, v4, v5, s61
	ds_write_b16_d16_hi v15, v4 offset:384
	v_mul_f32_e32 v4, v53, v16
	v_bfe_u32 v5, v4, 16, 1
	v_add3_u32 v4, v4, v5, s61
	ds_write_b16_d16_hi v15, v4 offset:448
	v_mul_f32_e32 v4, v38, v17
	v_bfe_u32 v5, v4, 16, 1
	v_add3_u32 v4, v4, v5, s61
	ds_write_b16_d16_hi v15, v4 offset:1024
	v_mul_f32_e32 v4, v54, v17
	v_bfe_u32 v5, v4, 16, 1
	v_add3_u32 v4, v4, v5, s61
	ds_write_b16_d16_hi v15, v4 offset:1088
	v_mul_f32_e32 v4, v39, v66
	v_bfe_u32 v5, v4, 16, 1
	v_add3_u32 v4, v4, v5, s61
	ds_write_b16_d16_hi v15, v4 offset:1152
	v_mul_f32_e32 v4, v55, v66
	v_bfe_u32 v5, v4, 16, 1
	v_add3_u32 v4, v4, v5, s61
	ds_write_b16_d16_hi v15, v4 offset:1216
	v_mul_f32_e32 v4, v40, v67
	v_bfe_u32 v5, v4, 16, 1
	v_add3_u32 v4, v4, v5, s61
	ds_write_b16_d16_hi v15, v4 offset:1280
	v_mul_f32_e32 v4, v56, v67
	v_bfe_u32 v5, v4, 16, 1
	v_add3_u32 v4, v4, v5, s61
	ds_write_b16_d16_hi v15, v4 offset:1344
	v_mul_f32_e32 v4, v41, v68
	v_bfe_u32 v5, v4, 16, 1
	v_add3_u32 v4, v4, v5, s61
	ds_write_b16_d16_hi v15, v4 offset:1408
	v_mul_f32_e32 v4, v57, v68
	v_bfe_u32 v5, v4, 16, 1
	v_add3_u32 v4, v4, v5, s61
	ds_write_b16_d16_hi v15, v4 offset:1472
	v_mul_f32_e32 v4, v42, v3
	v_bfe_u32 v5, v4, 16, 1
	v_add3_u32 v4, v4, v5, s61
	v_mul_f32_e32 v3, v58, v3
	ds_write_b16_d16_hi v15, v4 offset:2048
	v_bfe_u32 v4, v3, 16, 1
	v_add3_u32 v3, v3, v4, s61
	ds_write_b16_d16_hi v15, v3 offset:2112
	v_mul_f32_e32 v3, v43, v8
	v_bfe_u32 v4, v3, 16, 1
	v_add3_u32 v3, v3, v4, s61
	ds_write_b16_d16_hi v15, v3 offset:2176
	v_mul_f32_e32 v3, v59, v8
	v_bfe_u32 v4, v3, 16, 1
	v_add3_u32 v3, v3, v4, s61
	ds_write_b16_d16_hi v15, v3 offset:2240
	v_mul_f32_e32 v3, v44, v9
	v_bfe_u32 v4, v3, 16, 1
	v_add3_u32 v3, v3, v4, s61
	ds_write_b16_d16_hi v15, v3 offset:2304
	v_mul_f32_e32 v3, v60, v9
	v_bfe_u32 v4, v3, 16, 1
	v_add3_u32 v3, v3, v4, s61
	ds_write_b16_d16_hi v15, v3 offset:2368
	v_mul_f32_e32 v3, v45, v10
	v_bfe_u32 v4, v3, 16, 1
	v_add3_u32 v3, v3, v4, s61
	ds_write_b16_d16_hi v15, v3 offset:2432
	v_mul_f32_e32 v3, v61, v10
	v_bfe_u32 v4, v3, 16, 1
	v_add3_u32 v3, v3, v4, s61
	ds_write_b16_d16_hi v15, v3 offset:2496
	v_mul_f32_e32 v3, v46, v11
	v_bfe_u32 v4, v3, 16, 1
	v_add3_u32 v3, v3, v4, s61
	ds_write_b16_d16_hi v15, v3 offset:3072
	v_mul_f32_e32 v3, v62, v11
	v_bfe_u32 v4, v3, 16, 1
	v_add3_u32 v3, v3, v4, s61
	ds_write_b16_d16_hi v15, v3 offset:3136
	v_mul_f32_e32 v3, v47, v12
	v_bfe_u32 v4, v3, 16, 1
	v_add3_u32 v3, v3, v4, s61
	ds_write_b16_d16_hi v15, v3 offset:3200
	v_mul_f32_e32 v3, v63, v12
	v_bfe_u32 v4, v3, 16, 1
	v_add3_u32 v3, v3, v4, s61
	ds_write_b16_d16_hi v15, v3 offset:3264
	v_mul_f32_e32 v3, v48, v13
	v_bfe_u32 v4, v3, 16, 1
	v_add3_u32 v3, v3, v4, s61
	ds_write_b16_d16_hi v15, v3 offset:3328
	v_mul_f32_e32 v3, v64, v13
	v_bfe_u32 v4, v3, 16, 1
	v_add3_u32 v3, v3, v4, s61
	ds_write_b16_d16_hi v15, v3 offset:3392
	v_mul_f32_e32 v3, v49, v14
	v_bfe_u32 v4, v3, 16, 1
	v_add3_u32 v3, v3, v4, s61
	ds_write_b16_d16_hi v15, v3 offset:3456
	v_mul_f32_e32 v3, v65, v14
	v_bfe_u32 v4, v3, 16, 1
	v_add3_u32 v3, v3, v4, s61
	ds_write_b16_d16_hi v15, v3 offset:3520
	v_lshlrev_b32_e32 v3, 1, v214
	v_and_b32_e32 v4, 0x70, v3
	v_lshrrev_b32_e32 v1, 3, v1
	v_add_u32_e32 v3, s24, v4
	s_waitcnt lgkmcnt(0)
	v_mov_b32_e32 v5, v2
	v_lshl_add_u32 v7, v1, 7, v3
	v_lshl_add_u64 v[4:5], s[4:5], 0, v[4:5]
	ds_read_b128 v[8:11], v7
	v_lshlrev_b32_e32 v12, 10, v1
	v_mov_b32_e32 v13, v2
	v_or_b32_e32 v7, 8, v1
	v_lshl_add_u64 v[16:17], v[4:5], 0, v[12:13]
	v_lshl_add_u32 v12, v7, 7, v3
	ds_read_b128 v[12:15], v12
	s_waitcnt lgkmcnt(1)
	global_store_dwordx4 v[16:17], v[8:11], off sc0 sc1
	s_nop 1
	v_lshlrev_b32_e32 v8, 10, v7
	v_mov_b32_e32 v9, v2
	v_lshl_add_u64 v[8:9], v[4:5], 0, v[8:9]
	v_or_b32_e32 v7, 16, v1
	s_waitcnt lgkmcnt(0)
	global_store_dwordx4 v[8:9], v[12:15], off sc0 sc1
	v_lshl_add_u32 v8, v7, 7, v3
	ds_read_b128 v[8:11], v8
	v_or_b32_e32 v1, 24, v1
	v_lshlrev_b32_e32 v12, 10, v7
	v_mov_b32_e32 v13, v2
	v_lshl_add_u32 v3, v1, 7, v3
	v_lshl_add_u64 v[16:17], v[4:5], 0, v[12:13]
	ds_read_b128 v[12:15], v3
	s_waitcnt lgkmcnt(1)
	global_store_dwordx4 v[16:17], v[8:11], off sc0 sc1
	s_nop 1
	v_lshlrev_b32_e32 v8, 10, v1
	v_mov_b32_e32 v9, v2
	v_lshl_add_u64 v[4:5], v[4:5], 0, v[8:9]
	s_waitcnt lgkmcnt(0)
	global_store_dwordx4 v[4:5], v[12:15], off sc0 sc1
	s_waitcnt lgkmcnt(0)
	s_barrier

.LBB0_1158:
	v_add_f32_e32 v8, v82, v83
	v_add_f32_e32 v8, v84, v8
	v_add_f32_e32 v8, v85, v8
	v_add_f32_e32 v8, v86, v8
	v_add_f32_e32 v8, v87, v8
	v_add_f32_e32 v8, v88, v8
	v_add_f32_e32 v8, v89, v8
	v_add_f32_e32 v8, v90, v8
	v_add_f32_e32 v8, v91, v8
	v_add_f32_e32 v8, v92, v8
	v_add_f32_e32 v8, v93, v8
	v_add_f32_e32 v8, v94, v8
	v_add_f32_e32 v8, v95, v8
	v_add_f32_e32 v8, v96, v8
	v_add_f32_e32 v8, v97, v8
	v_add_f32_e32 v8, v66, v8
	v_add_f32_e32 v8, v67, v8
	v_add_f32_e32 v8, v68, v8
	v_add_f32_e32 v8, v69, v8
	v_add_f32_e32 v8, v70, v8
	v_add_f32_e32 v8, v71, v8
	v_add_f32_e32 v8, v72, v8
	v_add_f32_e32 v8, v73, v8
	v_add_f32_e32 v8, v74, v8
	v_add_f32_e32 v8, v75, v8
	v_add_f32_e32 v8, v76, v8
	v_add_f32_e32 v8, v77, v8
	v_add_f32_e32 v8, v78, v8
	s_cmp_lg_u32 0, -1
	v_add_f32_e32 v8, v79, v8
	s_cselect_b32 s33, 0, 0
	v_add_f32_e32 v8, v80, v8
	s_addk_i32 s33, 0x6000
	v_add_f32_e32 v8, v81, v8
	v_add3_u32 v5, v217, s33, v215
	v_add_f32_e32 v4, v4, v8
	v_cvt_pk_bf16_f32 v8, v82, v83
	v_cvt_pk_bf16_f32 v9, v84, v85
	v_cvt_pk_bf16_f32 v10, v86, v87
	v_cvt_pk_bf16_f32 v11, v88, v89
	v_cvt_pk_bf16_f32 v12, v90, v91
	v_cvt_pk_bf16_f32 v13, v92, v93
	v_cvt_pk_bf16_f32 v14, v94, v95
	v_cvt_pk_bf16_f32 v15, v96, v97
	v_cvt_pk_bf16_f32 v66, v66, v67
	v_cvt_pk_bf16_f32 v67, v68, v69
	v_cvt_pk_bf16_f32 v68, v70, v71
	v_cvt_pk_bf16_f32 v69, v72, v73
	v_cvt_pk_bf16_f32 v70, v74, v75
	v_cvt_pk_bf16_f32 v71, v76, v77
	v_cvt_pk_bf16_f32 v72, v78, v79
	v_cvt_pk_bf16_f32 v73, v80, v81
	v_add3_u32 v5, v5, v216, s65
	ds_read_b64_tr_b16 v[74:75],v5 offset:0
	ds_read_b64_tr_b16 v[76:77],v5 offset:512
	ds_read_b64_tr_b16 v[78:79],v5 offset:1024
	ds_read_b64_tr_b16 v[80:81],v5 offset:1536
	ds_read_b64_tr_b16 v[82:83],v5 offset:2048
	ds_read_b64_tr_b16 v[84:85],v5 offset:2560
	ds_read_b64_tr_b16 v[86:87],v5 offset:3072
	ds_read_b64_tr_b16 v[88:89],v5 offset:3584
	s_waitcnt lgkmcnt(0)
	s_nop 0
	v_mfma_f32_32x32x16_bf16 v[34:49], v[8:11], v[74:77], v[34:49]
	ds_read_b64_tr_b16 v[74:75],v5 offset:4096
	ds_read_b64_tr_b16 v[76:77],v5 offset:4608
	v_mfma_f32_32x32x16_bf16 v[34:49], v[12:15], v[78:81], v[34:49]
	ds_read_b64_tr_b16 v[78:79],v5 offset:5120
	ds_read_b64_tr_b16 v[80:81],v5 offset:5632
	v_mfma_f32_32x32x16_bf16 v[34:49], v[66:69], v[82:85], v[34:49]
	ds_read_b64_tr_b16 v[82:83],v5 offset:6144
	ds_read_b64_tr_b16 v[84:85],v5 offset:6656
	ds_read_b64_tr_b16 v[90:91],v5 offset:7168
	ds_read_b64_tr_b16 v[92:93],v5 offset:7680
	s_waitcnt lgkmcnt(0)
	v_mfma_f32_32x32x16_bf16 v[34:49], v[70:73], v[86:89], v[34:49]
	v_mfma_f32_32x32x16_bf16 v[50:65], v[8:11], v[74:77], v[50:65]
	v_mov_b32_e32 v5, v4
	s_nop 1
	v_permlane32_swap_b32_e32 v4, v5
	v_mfma_f32_32x32x16_bf16 v[50:65], v[12:15], v[78:81], v[50:65]
	v_mfma_f32_32x32x16_bf16 v[50:65], v[66:69], v[82:85], v[50:65]
	v_mfma_f32_32x32x16_bf16 v[50:65], v[70:73], v[90:93], v[50:65]
	s_and_saveexec_b64 s[38:39], s[4:5]
	v_add_f32_e32 v4, v4, v5
	ds_write_b32 v218, v4 offset:49280
	s_or_b64 exec, exec, s[38:39]
	s_waitcnt lgkmcnt(0)
	ds_read_b128 v[8:11], v222 offset:49280
	ds_read_b128 v[12:15], v222 offset:49312
	s_add_i32 s4, s63, 0
	v_lshlrev_b32_e32 v70, 9, v214
	v_lshlrev_b32_e32 v7, 1, v7
	s_waitcnt lgkmcnt(1)
	v_rcp_f32_e32 v4, v8
	v_rcp_f32_e32 v5, v9
	v_add3_u32 v7, s4, v70, v7
	v_rcp_f32_e32 v16, v10
	v_mul_f32_e32 v34, v34, v4
	v_bfe_u32 v70, v34, 16, 1
	v_add3_u32 v34, v34, v70, s61
	v_mul_f32_e32 v4, v50, v4
	ds_write_b16_d16_hi v7, v34 offset:51200
	v_bfe_u32 v34, v4, 16, 1
	v_add3_u32 v4, v4, v34, s61
	ds_write_b16_d16_hi v7, v4 offset:51264
	v_mul_f32_e32 v4, v35, v5
	v_bfe_u32 v34, v4, 16, 1
	v_add3_u32 v4, v4, v34, s61
	ds_write_b16_d16_hi v7, v4 offset:51328
	v_mul_f32_e32 v4, v51, v5
	v_bfe_u32 v5, v4, 16, 1
	v_add3_u32 v4, v4, v5, s61
	ds_write_b16_d16_hi v7, v4 offset:51392
	v_mul_f32_e32 v4, v36, v16
	v_bfe_u32 v5, v4, 16, 1
	v_rcp_f32_e32 v17, v11
	v_add3_u32 v4, v4, v5, s61
	ds_write_b16_d16_hi v7, v4 offset:51456
	v_mul_f32_e32 v4, v52, v16
	v_bfe_u32 v5, v4, 16, 1
	v_add3_u32 v4, v4, v5, s61
	ds_write_b16_d16_hi v7, v4 offset:51520
	v_mul_f32_e32 v4, v37, v17
	v_bfe_u32 v5, v4, 16, 1
	s_waitcnt lgkmcnt(6)
	v_rcp_f32_e32 v66, v12
	v_add3_u32 v4, v4, v5, s61
	ds_write_b16_d16_hi v7, v4 offset:51584
	v_mul_f32_e32 v4, v53, v17
	v_bfe_u32 v5, v4, 16, 1
	v_add3_u32 v4, v4, v5, s61
	ds_write_b16_d16_hi v7, v4 offset:51648
	v_mul_f32_e32 v4, v38, v66
	v_bfe_u32 v5, v4, 16, 1
	v_rcp_f32_e32 v67, v13
	v_add3_u32 v4, v4, v5, s61
	ds_write_b16_d16_hi v7, v4 offset:52224
	v_mul_f32_e32 v4, v54, v66
	v_bfe_u32 v5, v4, 16, 1
	v_add3_u32 v4, v4, v5, s61
	ds_write_b16_d16_hi v7, v4 offset:52288
	v_mul_f32_e32 v4, v39, v67
	v_bfe_u32 v5, v4, 16, 1
	v_rcp_f32_e32 v68, v14
	v_add3_u32 v4, v4, v5, s61
	ds_write_b16_d16_hi v7, v4 offset:52352
	v_mul_f32_e32 v4, v55, v67
	v_bfe_u32 v5, v4, 16, 1
	v_add3_u32 v4, v4, v5, s61
	ds_write_b16_d16_hi v7, v4 offset:52416
	v_mul_f32_e32 v4, v40, v68
	v_bfe_u32 v5, v4, 16, 1
	v_rcp_f32_e32 v69, v15
	v_add3_u32 v4, v4, v5, s61
	ds_read_b128 v[8:11], v222 offset:49344
	ds_read_b128 v[12:15], v222 offset:49376
	ds_write_b16_d16_hi v7, v4 offset:52480
	v_mul_f32_e32 v4, v56, v68
	v_bfe_u32 v5, v4, 16, 1
	v_add3_u32 v4, v4, v5, s61
	ds_write_b16_d16_hi v7, v4 offset:52544
	v_mul_f32_e32 v4, v41, v69
	v_bfe_u32 v5, v4, 16, 1
	s_waitcnt lgkmcnt(3)
	v_rcp_f32_e32 v8, v8
	v_add3_u32 v4, v4, v5, s61
	ds_write_b16_d16_hi v7, v4 offset:52608
	v_mul_f32_e32 v4, v57, v69
	v_bfe_u32 v5, v4, 16, 1
	v_add3_u32 v4, v4, v5, s61
	ds_write_b16_d16_hi v7, v4 offset:52672
	v_mul_f32_e32 v4, v42, v8
	v_bfe_u32 v5, v4, 16, 1
	v_rcp_f32_e32 v9, v9
	v_add3_u32 v4, v4, v5, s61
	ds_write_b16_d16_hi v7, v4 offset:53248
	v_mul_f32_e32 v4, v58, v8
	v_bfe_u32 v5, v4, 16, 1
	v_add3_u32 v4, v4, v5, s61
	ds_write_b16_d16_hi v7, v4 offset:53312
	v_mul_f32_e32 v4, v43, v9
	v_bfe_u32 v5, v4, 16, 1
	v_rcp_f32_e32 v10, v10
	v_add3_u32 v4, v4, v5, s61
	ds_write_b16_d16_hi v7, v4 offset:53376
	v_mul_f32_e32 v4, v59, v9
	v_bfe_u32 v5, v4, 16, 1
	v_add3_u32 v4, v4, v5, s61
	ds_write_b16_d16_hi v7, v4 offset:53440
	v_mul_f32_e32 v4, v44, v10
	v_bfe_u32 v5, v4, 16, 1
	v_rcp_f32_e32 v11, v11
	v_add3_u32 v4, v4, v5, s61
	ds_write_b16_d16_hi v7, v4 offset:53504
	v_mul_f32_e32 v4, v60, v10
	v_bfe_u32 v5, v4, 16, 1
	v_add3_u32 v4, v4, v5, s61
	ds_write_b16_d16_hi v7, v4 offset:53568
	v_mul_f32_e32 v4, v45, v11
	v_bfe_u32 v5, v4, 16, 1
	s_waitcnt lgkmcnt(10)
	v_rcp_f32_e32 v12, v12
	v_add3_u32 v4, v4, v5, s61
	ds_write_b16_d16_hi v7, v4 offset:53632
	v_mul_f32_e32 v4, v61, v11
	v_bfe_u32 v5, v4, 16, 1
	v_add3_u32 v4, v4, v5, s61
	ds_write_b16_d16_hi v7, v4 offset:53696
	v_mul_f32_e32 v4, v46, v12
	v_bfe_u32 v5, v4, 16, 1
	v_rcp_f32_e32 v13, v13
	v_add3_u32 v4, v4, v5, s61
	ds_write_b16_d16_hi v7, v4 offset:54272
	v_mul_f32_e32 v4, v62, v12
	v_bfe_u32 v5, v4, 16, 1
	v_add3_u32 v4, v4, v5, s61
	ds_write_b16_d16_hi v7, v4 offset:54336
	v_mul_f32_e32 v4, v47, v13
	v_bfe_u32 v5, v4, 16, 1
	v_rcp_f32_e32 v14, v14
	v_add3_u32 v4, v4, v5, s61
	ds_write_b16_d16_hi v7, v4 offset:54400
	v_mul_f32_e32 v4, v63, v13
	v_bfe_u32 v5, v4, 16, 1
	v_add3_u32 v4, v4, v5, s61
	ds_write_b16_d16_hi v7, v4 offset:54464
	v_mul_f32_e32 v4, v48, v14
	v_bfe_u32 v5, v4, 16, 1
	v_rcp_f32_e32 v15, v15
	v_add3_u32 v4, v4, v5, s61
	ds_write_b16_d16_hi v7, v4 offset:54528
	v_mul_f32_e32 v4, v64, v14
	v_bfe_u32 v5, v4, 16, 1
	v_add3_u32 v4, v4, v5, s61
	ds_write_b16_d16_hi v7, v4 offset:54592
	v_mul_f32_e32 v4, v49, v15
	v_bfe_u32 v5, v4, 16, 1
	v_add3_u32 v4, v4, v5, s61
	ds_write_b16_d16_hi v7, v4 offset:54656
	v_mul_f32_e32 v4, v65, v15
	v_bfe_u32 v5, v4, 16, 1
	v_add3_u32 v4, v4, v5, s61
	v_lshlrev_b32_e32 v3, 1, v3
	ds_write_b16_d16_hi v7, v4 offset:54720
	v_and_b32_e32 v4, 0x70, v3
	v_lshrrev_b32_e32 v1, 3, v1
	v_add_u32_e32 v3, s4, v4
	s_waitcnt lgkmcnt(0)
	v_mov_b32_e32 v5, v2
	v_lshl_add_u32 v7, v1, 7, v3
	v_lshl_add_u64 v[4:5], s[36:37], 0, v[4:5]
	ds_read_b128 v[8:11], v7 offset:51200
	v_lshlrev_b32_e32 v12, 10, v1
	v_mov_b32_e32 v13, v2
	v_or_b32_e32 v7, 8, v1
	v_lshl_add_u64 v[16:17], v[4:5], 0, v[12:13]
	v_lshl_add_u32 v12, v7, 7, v3
	ds_read_b128 v[12:15], v12 offset:51200
	s_waitcnt lgkmcnt(1)
	global_store_dwordx4 v[16:17], v[8:11], off sc0 sc1
	s_mov_b64 s[4:5], 0
	s_nop 0
	v_lshlrev_b32_e32 v8, 10, v7
	v_mov_b32_e32 v9, v2
	v_lshl_add_u64 v[8:9], v[4:5], 0, v[8:9]
	v_or_b32_e32 v7, 16, v1
	s_waitcnt lgkmcnt(0)
	global_store_dwordx4 v[8:9], v[12:15], off sc0 sc1
	v_lshl_add_u32 v8, v7, 7, v3
	ds_read_b128 v[8:11], v8 offset:51200
	v_or_b32_e32 v1, 24, v1
	v_lshlrev_b32_e32 v12, 10, v7
	v_mov_b32_e32 v13, v2
	v_lshl_add_u32 v3, v1, 7, v3
	v_lshl_add_u64 v[16:17], v[4:5], 0, v[12:13]
	ds_read_b128 v[12:15], v3 offset:51200
	s_waitcnt lgkmcnt(1)
	global_store_dwordx4 v[16:17], v[8:11], off sc0 sc1
	s_nop 1
	v_lshlrev_b32_e32 v8, 10, v1
	v_mov_b32_e32 v9, v2
	v_lshl_add_u64 v[4:5], v[4:5], 0, v[8:9]
	s_waitcnt lgkmcnt(0)
	global_store_dwordx4 v[4:5], v[12:15], off sc0 sc1
	s_waitcnt lgkmcnt(0)
	s_barrier
